# attention: same P.V/partial-softmax interleave in the second half-iteration; exp results kept in dead VGPRs across the loop edge with entry/exit copies
# speedup vs baseline: 1.0247x; 1.0020x over previous
; __device__ __forceinline__ int tid_() { int t = threadIdx.x; asm volatile("" : "+v"(t)); return t; }
; __device__ __forceinline__ int v_st(int k, int c) { const int kk = (k & ~0xC) | ((k & 4) << 1) | ((k & 8) >> 1); return ((kk >> 3) * 4 + (c >> 5)) * 512 + ((kk & 7) * 32 + (c & 31)) * 2; }
; __device__ __forceinline__ int v_rd_base(int lane) { return ((lane & 3) << 3) | (((lane >> 2) & 3) << 6) | (((lane >> 4) & 1) << 5) | (((lane >> 5) & 1) << 8); }
; #define SWRITE(b, i) do { *(bf16x8*)(V_lds + (b) * SHM_V + vst0) = sr_[i].vs0;          \
;     *(bf16x8*)(V_lds + (b) * SHM_V + vst1) = sr_[i].vs1; int kc = sc * 2;               \
;     *(bf16x8*)(K_lds + (b) * SHM_K + KSWZ(sr, kc)) = sr_[i].ks0;                       \
;     *(bf16x8*)(K_lds + (b) * SHM_K + KSWZ(32 + sr, kc)) = sr_[i].ks1; } while (0)
; __device__ __forceinline__ void attn_unit(const bf16_t* Qb, const bf16_t* Kh, const bf16_t* Vh, bf16_t* Ob, float* scr, int seq, float lam, float onemli, const float* subg, char* lds) {
;     const int tid = tid_(), wid = tid >> 6, lane = tid & 63, r32 = lane & 31, hi = lane >> 5;
;     char* V_lds = lds; char* K_lds = lds + 2 * SHM_V;
;     float* wsl = (float*)(lds + 2 * SHM_V + 2 * SHM_K) + wid * 64; float* li_l = wsl; float* al_l = wsl + 32;
;     const int sr = tid >> 4, sc = (tid & 15) * 8, vst0 = v_st(sr, sc), vst1 = v_st(32 + sr, sc);
;     const unsigned kvoff = (unsigned)(sr * LD + sc) * 2u;
;     const int vb0 = (int)(uintptr_t)V_lds + v_rd_base(lane);
;     const int NT = seq / KVBLK;
; #pragma unroll
;     for (int comp = 0; comp < 2; ++comp) {
;         float m_reg = -1e30f, l_reg = 0; f32x16 o[4] = {}; bf16x8 qr[4];
;         const unsigned qoff = (unsigned)((wid * 32 + r32) * LD + comp * 64 + hi * 8) * 2u;
; #pragma unroll
;         for (int d0 = 0; d0 < 4; ++d0) qr[d0] = *reinterpret_cast<const bf16x8*>((const char*)Qb + qoff + d0 * 32);
;         struct { bf16x8 vs0, vs1, ks0, ks1; } sr_[1];
;     ...
;         f32x16 pA0, pA1, pB0, pB1; float mnA, mnB, alA, alB; bf16x8 pa0, pa1, pa2, pa3;
;         constexpr int SE = 0, SO = 0;
;         __syncthreads();
;         SLOAD(SE, 0); asm volatile("s_waitcnt vmcnt(0)" ::: "memory"); SWRITE(0, SE); __syncthreads();
;         qkt(pA0, pA1, K_lds, qr, r32, hi, comp); partialSM(pA0, pA1, m_reg, mnA, alA);
;         SLOAD(SO, KVBLK);
;         SWAIT(); SWRITE(1, SO); __syncthreads();
.LBB0_261:
	s_lshl_b32 s26, s26, 8
	s_ashr_i32 s6, s9, 3
	s_addk_i32 s26, 0x100
	s_and_b64 s[2:3], exec, s[2:3]
	s_mul_i32 s8, s6, 0x1100
	s_cselect_b32 s2, 0, s26
	s_mul_hi_i32 s7, s6, 0x1100
	s_add_u32 s2, s8, s2
	s_addc_u32 s3, s7, 0
	s_lshl_b64 s[26:27], s[2:3], 10
	s_lshl_b64 s[2:3], s[2:3], 11
	s_add_u32 s2, s14, s2
	s_addc_u32 s3, s15, s3
	s_lshl_b32 s7, s9, 7
	s_and_b32 s66, s7, 0x380
	s_lshl_b32 s7, s66, 1
	s_add_u32 s2, s2, s7
	s_addc_u32 s3, s3, 0
	s_mul_hi_i32 s8, s6, 0x880000
	s_mul_i32 s6, s6, 0x880000
	s_add_u32 s9, s16, s6
	s_addc_u32 s29, s17, s8
	s_add_u32 s28, s9, s7
	s_addc_u32 s29, s29, 0
	v_mov_b32_e32 v165, v252
	s_add_u32 s6, s18, s6
	s_addc_u32 s8, s19, s8
	v_ashrrev_i32_e32 v150, 6, v165
	v_lshlrev_b32_e32 v17, 3, v165
	v_and_b32_e32 v155, 31, v165
	v_bfe_u32 v152, v165, 5, 1
	v_and_b32_e32 v0, 0x78, v17
	v_lshlrev_b32_e32 v153, 5, v150
	s_add_u32 s58, s6, s7
	v_ashrrev_i32_e32 v16, 4, v165
	v_lshlrev_b32_e32 v18, 1, v0
	v_or_b32_e32 v0, v153, v155
	v_lshlrev_b32_e32 v166, 4, v152
	s_addc_u32 s59, s8, 0
	v_lshl_or_b32 v96, v16, 11, v18
	v_lshl_or_b32 v64, v0, 11, v166
	v_add_u32_e32 v66, 0x10000, v96
	global_load_dwordx4 v[110:113], v64, s[2:3]
	global_load_dwordx4 v[106:109], v64, s[2:3] offset:32
	global_load_dwordx4 v[102:105], v64, s[2:3] offset:64
	global_load_dwordx4 v[98:101], v64, s[2:3] offset:96
	s_barrier
	global_load_dwordx4 v[0:3], v96, s[58:59]
	global_load_dwordx4 v[4:7], v66, s[58:59]
	global_load_dwordx4 v[8:11], v96, s[28:29]
	global_load_dwordx4 v[12:15], v66, s[28:29]
	v_and_b32_e32 v154, 63, v165
	v_lshlrev_b32_e32 v156, 4, v165
	v_and_b32_e32 v22, 0xfffff0, v16
	v_lshlrev_b32_e32 v23, 1, v16
	v_lshrrev_b32_e32 v24, 1, v16
	v_and_b32_e32 v25, 3, v16
	v_add_u32_e32 v26, 32, v16
	v_lshlrev_b32_e32 v20, 1, v165
	v_lshlrev_b32_e32 v27, 3, v154
	v_and_b32_e32 v28, 0xc0, v156
	v_and_or_b32 v22, v23, 8, v22
	v_and_or_b32 v23, v24, 4, v25
	v_and_b32_e32 v24, 0xfffff0, v26
	v_lshlrev_b32_e32 v25, 1, v26
	v_and_b32_e32 v21, 0x70, v165
	v_bfe_u32 v17, v17, 5, 2
	v_and_b32_e32 v20, 32, v20
	v_lshlrev_b32_e32 v16, 8, v16
	v_and_or_b32 v28, v27, 24, v28
	v_and_b32_e32 v27, 0x100, v27
	v_lshlrev_b32_e32 v26, 8, v26
	v_lshrrev_b32_e32 v22, 1, v22
	v_and_or_b32 v24, v25, 8, v24
	v_and_b32_e32 v29, 48, v18
	v_or3_b32 v65, v28, v20, v27
	v_bitop3_b32 v16, v18, v16, v21 bitop3:0xde
	v_bitop3_b32 v18, v18, v26, v21 bitop3:0xde
	v_or_b32_e32 v20, v22, v17
	v_lshrrev_b32_e32 v21, 1, v24
	v_lshlrev_b32_e32 v23, 6, v23
	v_add_u32_e32 v161, 0, v16
	v_lshlrev_b32_e32 v16, 9, v20
	v_or_b32_e32 v17, v21, v17
	v_or3_b32 v16, v16, v23, v29
	v_lshlrev_b32_e32 v17, 9, v17
	v_lshlrev_b32_e32 v167, 8, v155
	v_and_b32_e32 v168, 0x70, v156
	v_or3_b32 v17, v17, v23, v29
	v_add_u32_e32 v163, 0, v16
	v_add_u32_e32 v162, 0, v18
	v_add_u32_e32 v164, 0, v17
	s_waitcnt vmcnt(0)
	v_and_b32_e32 v19, 0x3fffffc0, v165
	s_add_i32 s6, 0, 0x10000
	v_lshl_add_u32 v68, v19, 2, s6
	s_cmp_lg_u32 0, -1
	s_cselect_b32 s8, 0, 0
	v_add_u32_e32 v160, s8, v65
	s_addk_i32 s8, 0x4000
	v_mov_b32_e32 v67, v97
	v_add_u32_e32 v159, s8, v65
	v_mov_b32_e32 v65, v97
	v_lshl_add_u64 v[142:143], s[58:59], 0, v[66:67]
	s_waitcnt vmcnt(3)
	ds_write_b128 v163, v[0:3]
	s_waitcnt vmcnt(2)
	ds_write_b128 v164, v[4:7]
	s_waitcnt vmcnt(1)
	ds_write_b128 v161, v[8:11] offset:32768
	s_waitcnt vmcnt(0)
	ds_write_b128 v162, v[12:15] offset:32768
	v_bitop3_b32 v0, v166, v167, v168 bitop3:0xde
	v_add_u32_e32 v170, 0, v0
	s_waitcnt lgkmcnt(0)
	s_barrier
	ds_read_b128 v[0:3], v170 offset:32768
	ds_read_b128 v[4:7], v170 offset:40960
	s_waitcnt lgkmcnt(1)
	v_mfma_f32_32x32x16_bf16 v[16:31], v[0:3], v[110:113], 0
	v_or_b32_e32 v0, 32, v166
	v_bitop3_b32 v0, v0, v167, v168 bitop3:0xde
	v_add_u32_e32 v8, 0x20000, v96
	v_add_u32_e32 v171, 0, v0
	v_add_u32_e32 v10, 0x30000, v96
	ds_read_b128 v[0:3], v171 offset:32768
	global_load_dwordx4 v[48:51], v8, s[58:59]
	global_load_dwordx4 v[52:55], v10, s[58:59]
	global_load_dwordx4 v[56:59], v8, s[28:29]
	global_load_dwordx4 v[60:63], v10, s[28:29]
	s_waitcnt lgkmcnt(0)
	v_mfma_f32_32x32x16_bf16 v[16:31], v[0:3], v[106:109], v[16:31]
	v_or_b32_e32 v0, 64, v166
	v_bitop3_b32 v0, v0, v167, v168 bitop3:0xde
	v_add_u32_e32 v173, 0, v0
	ds_read_b128 v[0:3], v173 offset:32768
	v_lshl_add_u64 v[146:147], s[28:29], 0, v[66:67]
	v_lshl_add_u64 v[148:149], s[2:3], 0, v[64:65]
	v_mov_b32_e32 v9, v97
	v_mfma_f32_32x32x16_bf16 v[32:47], v[4:7], v[110:113], 0
	ds_read_b128 v[4:7], v171 offset:40960
	v_mov_b32_e32 v11, v97
	s_mov_b32 s36, s37
	v_lshl_add_u64 v[132:133], s[58:59], 0, v[8:9]
	v_lshl_add_u64 v[138:139], s[58:59], 0, v[10:11]
	v_lshl_add_u64 v[134:135], s[28:29], 0, v[8:9]
	v_lshl_add_u64 v[136:137], s[28:29], 0, v[10:11]
	s_waitcnt lgkmcnt(1)
	v_mfma_f32_32x32x16_bf16 v[16:31], v[0:3], v[102:105], v[16:31]
	v_or_b32_e32 v0, 0x60, v166
	v_bitop3_b32 v0, v0, v167, v168 bitop3:0xde
	v_add_u32_e32 v172, 0, v0
	ds_read_b128 v[0:3], v172 offset:32768
	ds_read_b128 v[64:67], v172 offset:40960
	s_mov_b32 s38, s37
	s_mov_b32 s39, s37
	s_waitcnt lgkmcnt(2)
	v_mfma_f32_32x32x16_bf16 v[32:47], v[4:7], v[106:109], v[32:47]
	ds_read_b128 v[4:7], v173 offset:40960
	s_waitcnt vmcnt(0)
	s_mov_b32 s40, s37
	s_mov_b32 s41, s37
	s_mov_b32 s42, s37
	s_mov_b32 s43, s37
	s_mov_b32 s44, s37
	s_waitcnt lgkmcnt(0)
	v_mfma_f32_32x32x16_bf16 v[32:47], v[4:7], v[102:105], v[32:47]
	s_mov_b32 s45, s37
	s_mov_b32 s46, s37
	s_mov_b32 s47, s37
	s_waitcnt vmcnt(3)
	ds_write_b128 v163, v[48:51] offset:16384
	s_waitcnt vmcnt(2)
	ds_write_b128 v164, v[52:55] offset:16384
	s_waitcnt vmcnt(1)
	ds_write_b128 v161, v[56:59] offset:49152
	s_waitcnt vmcnt(0)
; #define SWRITE(b, i) do { *(bf16x8*)(V_lds + (b) * SHM_V + vst0) = sr_[i].vs0;          \
;     *(bf16x8*)(V_lds + (b) * SHM_V + vst1) = sr_[i].vs1; int kc = sc * 2;               \
;     *(bf16x8*)(K_lds + (b) * SHM_K + KSWZ(sr, kc)) = sr_[i].ks0;                       \
;     *(bf16x8*)(K_lds + (b) * SHM_K + KSWZ(32 + sr, kc)) = sr_[i].ks1; } while (0)
; #define SWAIT() asm volatile("s_waitcnt vmcnt(0)" ::: "memory")
; __device__ __forceinline__ void partialSM(f32x16& p0, f32x16& p1, float& m_reg, float& mn, float& alpha) {
;     constexpr float C = SCALE * 1.4426950408889634f;
;     float pmax = p0[0];
; #pragma unroll
;     for (int r = 1; r < 16; ++r) pmax = fmaxf(pmax, p0[r]);
; #pragma unroll
;     for (int r = 0; r < 16; ++r) pmax = fmaxf(pmax, p1[r]);
;     { auto rr = __builtin_amdgcn_permlane32_swap(__float_as_uint(pmax), __float_as_uint(pmax), false, false);
;       pmax = fmaxf(__uint_as_float(rr[0]), __uint_as_float(rr[1])); }
;     if (__builtin_expect(__all(pmax - m_reg <= THR / SCALE), 1)) { mn = m_reg; alpha = 1.f; }
;     else { mn = fmaxf(m_reg, pmax); alpha = __builtin_amdgcn_exp2f((m_reg - mn) * C); m_reg = mn; }
;     const float mnC = -mn * C;
; #pragma unroll
;     for (int r = 0; r < 16; ++r) p0[r] = fmaf(p0[r], C, mnC);
; #pragma unroll
;     for (int r = 0; r < 16; ++r) p1[r] = fmaf(p1[r], C, mnC);
; #pragma unroll
;     for (int r = 0; r < 16; ++r) p0[r] = __builtin_amdgcn_exp2f(p0[r]);
; }
; __device__ __forceinline__ void attn_unit(const bf16_t* Qb, const bf16_t* Kh, const bf16_t* Vh, bf16_t* Ob, float* scr, int seq, float lam, float onemli, const float* subg, char* lds) {
;     ...
;         SLOAD(SE, 0); asm volatile("s_waitcnt vmcnt(0)" ::: "memory"); SWRITE(0, SE); __syncthreads();
;         qkt(pA0, pA1, K_lds, qr, r32, hi, comp); partialSM(pA0, pA1, m_reg, mnA, alA);
;         SLOAD(SO, KVBLK);
;         SWAIT(); SWRITE(1, SO); __syncthreads();
	ds_write_b128 v162, v[60:63] offset:49152
	v_mfma_f32_32x32x16_bf16 v[16:31], v[0:3], v[98:101], v[16:31]
	s_mov_b32 s48, s37
	s_mov_b32 s49, s37
	s_mov_b32 s50, s37
	s_mov_b32 s51, s37
	v_mov_b64_e32 v[0:1], s[36:37]
	v_mov_b64_e32 v[14:15], s[50:51]
	v_lshl_add_u64 v[140:141], s[58:59], 0, v[96:97]
	v_mfma_f32_32x32x16_bf16 v[32:47], v[64:67], v[98:101], v[32:47]
	s_nop 3
	v_max_f32_e32 v64, v17, v17
	v_max_f32_e32 v65, v16, v16
	v_max_f32_e32 v64, v65, v64
	v_max3_f32 v64, v64, v18, v19
	v_max3_f32 v64, v64, v20, v21
	v_max3_f32 v64, v64, v22, v23
	v_max3_f32 v64, v64, v24, v25
	v_max3_f32 v64, v64, v26, v27
	v_max3_f32 v64, v64, v28, v29
	v_max3_f32 v64, v64, v30, v31
	v_max3_f32 v64, v64, v32, v33
	v_max3_f32 v64, v64, v34, v35
	v_max3_f32 v64, v64, v36, v37
	v_max3_f32 v64, v64, v38, v39
	v_max3_f32 v64, v64, v40, v41
	v_max3_f32 v64, v64, v42, v43
	v_max3_f32 v64, v64, v44, v45
	v_max3_f32 v64, v64, v46, v47
	v_mov_b32_e32 v65, v64
	s_nop 1
	v_permlane32_swap_b32_e32 v64, v65
	v_max_f32_e32 v65, v65, v65
	v_max_f32_e32 v64, v64, v64
	v_max_f32_e32 v64, v64, v65
	v_max_f32_e32 v48, 0xf149f2ca, v64
	v_sub_f32_e32 v49, 0xf149f2ca, v48
	v_mul_f32_e32 v49, 0x3e38aa3b, v49
	v_add_f32_e32 v65, 0x7149f2ca, v64
	v_exp_f32_e32 v49, v49
	v_cmp_ge_f32_e32 vcc, s65, v65
	s_cmp_eq_u64 vcc, exec
	s_cselect_b64 vcc, -1, 0
	v_cndmask_b32_e64 v174, v49, 1.0, vcc
	v_mov_b32_e32 v49, 0xf149f2ca
	v_cndmask_b32_e32 v175, v48, v49, vcc
	v_mul_f32_e32 v48, 0xbe38aa3b, v175
	v_fmamk_f32 v16, v16, 0x3e38aa3b, v48
	v_exp_f32_e32 v212, v16
	v_fmamk_f32 v16, v17, 0x3e38aa3b, v48
	v_exp_f32_e32 v216, v16
	v_fmamk_f32 v16, v18, 0x3e38aa3b, v48
	v_exp_f32_e32 v213, v16
	v_fmamk_f32 v16, v19, 0x3e38aa3b, v48
	v_exp_f32_e32 v217, v16
	v_fmamk_f32 v16, v20, 0x3e38aa3b, v48
	v_exp_f32_e32 v214, v16
	v_fmamk_f32 v16, v21, 0x3e38aa3b, v48
	v_exp_f32_e32 v218, v16
	v_fmamk_f32 v16, v22, 0x3e38aa3b, v48
	v_exp_f32_e32 v215, v16
	v_fmamk_f32 v16, v23, 0x3e38aa3b, v48
	v_exp_f32_e32 v219, v16
	v_fmamk_f32 v16, v24, 0x3e38aa3b, v48
	v_exp_f32_e32 v183, v16
	v_fmamk_f32 v16, v25, 0x3e38aa3b, v48
	v_exp_f32_e32 v187, v16
	v_fmamk_f32 v16, v26, 0x3e38aa3b, v48
	v_exp_f32_e32 v184, v16
	v_fmamk_f32 v16, v27, 0x3e38aa3b, v48
	v_exp_f32_e32 v188, v16
	v_fmamk_f32 v16, v28, 0x3e38aa3b, v48
	v_exp_f32_e32 v185, v16
	v_fmamk_f32 v16, v29, 0x3e38aa3b, v48
	v_pk_fma_f32 v[114:115], v[46:47], s[72:73], v[48:49] op_sel_hi:[1,0,0]
	v_pk_fma_f32 v[120:121], v[44:45], s[72:73], v[48:49] op_sel_hi:[1,0,0]
	v_pk_fma_f32 v[124:125], v[42:43], s[72:73], v[48:49] op_sel_hi:[1,0,0]
	v_pk_fma_f32 v[116:117], v[40:41], s[72:73], v[48:49] op_sel_hi:[1,0,0]
	v_pk_fma_f32 v[118:119], v[38:39], s[72:73], v[48:49] op_sel_hi:[1,0,0]
	v_pk_fma_f32 v[122:123], v[36:37], s[72:73], v[48:49] op_sel_hi:[1,0,0]
	v_pk_fma_f32 v[126:127], v[34:35], s[72:73], v[48:49] op_sel_hi:[1,0,0]
	v_pk_fma_f32 v[128:129], v[32:33], s[72:73], v[48:49] op_sel_hi:[1,0,0]
	v_exp_f32_e32 v189, v16
	v_fmamk_f32 v16, v30, 0x3e38aa3b, v48
	v_fmac_f32_e32 v48, 0x3e38aa3b, v31
	v_exp_f32_e32 v186, v16
	v_exp_f32_e32 v211, v48
	v_lshl_add_u64 v[144:145], s[28:29], 0, v[96:97]
	v_mov_b64_e32 v[2:3], s[38:39]
	v_mov_b64_e32 v[4:5], s[40:41]
	v_mov_b64_e32 v[6:7], s[42:43]
	v_mov_b64_e32 v[8:9], s[44:45]
	v_mov_b64_e32 v[10:11], s[46:47]
	v_mov_b64_e32 v[12:13], s[48:49]
	v_add_u32_e32 v96, 0x40000, v96
	v_mov_b64_e32 v[30:31], v[14:15]
	v_mov_b64_e32 v[46:47], v[14:15]
	v_mov_b64_e32 v[62:63], v[14:15]
	s_mov_b32 s76, 2
	v_cmp_gt_u32_e64 s[6:7], 32, v154
	v_lshl_add_u32 v157, v155, 2, v68
	v_add_u32_e32 v158, v68, v166
	v_mov_b32_e32 v169, 0
	v_mov_b32_e32 v176, v96
	v_mov_b64_e32 v[28:29], v[12:13]
	v_mov_b64_e32 v[26:27], v[10:11]
	v_mov_b64_e32 v[24:25], v[8:9]
	v_mov_b64_e32 v[22:23], v[6:7]
	v_mov_b64_e32 v[20:21], v[4:5]
	v_mov_b64_e32 v[18:19], v[2:3]
	v_mov_b64_e32 v[16:17], v[0:1]
	v_mov_b64_e32 v[44:45], v[12:13]
	v_mov_b64_e32 v[42:43], v[10:11]
	v_mov_b64_e32 v[40:41], v[8:9]
	v_mov_b64_e32 v[38:39], v[6:7]
	v_mov_b64_e32 v[36:37], v[4:5]
	v_mov_b64_e32 v[34:35], v[2:3]
	v_mov_b64_e32 v[32:33], v[0:1]
	v_mov_b64_e32 v[60:61], v[12:13]
	v_mov_b64_e32 v[58:59], v[10:11]
	v_mov_b64_e32 v[56:57], v[8:9]
	v_mov_b64_e32 v[54:55], v[6:7]
	v_mov_b64_e32 v[52:53], v[4:5]
	v_mov_b64_e32 v[50:51], v[2:3]
	v_mov_b64_e32 v[48:49], v[0:1]
	s_waitcnt lgkmcnt(0)
	s_barrier
	v_mov_b32_e32 v240, v212
	v_mov_b32_e32 v241, v216
	v_mov_b32_e32 v242, v213
	v_mov_b32_e32 v243, v217
	v_mov_b32_e32 v244, v214
	v_mov_b32_e32 v245, v218
	v_mov_b32_e32 v246, v215
	v_mov_b32_e32 v247, v219
	v_mov_b32_e32 v248, v183
	v_mov_b32_e32 v249, v187
	v_mov_b32_e32 v250, v184
	v_mov_b32_e32 v251, v188
	v_mov_b32_e32 v206, v185
	v_mov_b32_e32 v207, v189
	v_mov_b32_e32 v208, v186
	v_mov_b32_e32 v209, v211
; #define SBAR() __builtin_amdgcn_sched_barrier(0)
; __device__ __forceinline__ void finishSM(f32x16& p0, f32x16& p1, float alpha, float& l_reg, bf16x8& pa0, bf16x8& pa1, bf16x8& pa2, bf16x8& pa3) {
; #pragma unroll
;     for (int r = 0; r < 16; ++r) p1[r] = __builtin_amdgcn_exp2f(p1[r]);
;     float ps = 0;
; #pragma unroll
;     for (int r = 0; r < 16; ++r) ps += p0[r];
; #pragma unroll
;     for (int r = 0; r < 16; ++r) ps += p1[r];
;     { auto rr = __builtin_amdgcn_permlane32_swap(__float_as_uint(ps), __float_as_uint(ps), false, false);
;       ps = __uint_as_float(rr[0]) + __uint_as_float(rr[1]); }
;     l_reg = l_reg * alpha + ps;
;     ...
;     PK4(p0, 0, pa0); PK4(p0, 8, pa1); PK4(p1, 0, pa2); PK4(p1, 8, pa3);
;     ...
; }
; __device__ __forceinline__ void attn_unit(const bf16_t* Qb, const bf16_t* Kh, const bf16_t* Vh, bf16_t* Ob, float* scr, int seq, float lam, float onemli, const float* subg, char* lds) {
;     ...
;         for (int j = 1; j + 1 < NT; j += 2) {
;             SBAR(); qkt(pB0, pB1, K_lds + SHM_K, qr, r32, hi, comp);
;             finishSM(pA0, pA1, alA, l_reg, pa0, pa1, pa2, pa3); SBAR();
;             SLOAD(SO, (j + 1) * KVBLK); SBAR();
;             pv_d0(o, vb0, pa0, pa1, pa2, pa3); partialSM(pB0, pB1, m_reg, mnB, alB);
.LBB0_262:
	ds_read_b128 v[64:67], v170 offset:49152
	ds_read_b128 v[68:71], v170 offset:57344
	v_add_f32_e32 v177, 0, v240
	v_add_f32_e32 v177, v241, v177
	v_add_f32_e32 v177, v242, v177
	s_waitcnt lgkmcnt(1)
	v_mfma_f32_32x32x16_bf16 v[80:95], v[64:67], v[110:113], 0
	v_add_f32_e32 v177, v243, v177
	v_add_f32_e32 v177, v244, v177
	ds_read_b128 v[178:181], v171 offset:49152
	ds_read_b128 v[220:223], v171 offset:57344
	v_add_f32_e32 v177, v245, v177
	v_add_f32_e32 v177, v246, v177
	v_add_f32_e32 v177, v247, v177
	v_add_f32_e32 v177, v248, v177
	s_waitcnt lgkmcnt(2)
	v_mfma_f32_32x32x16_bf16 v[64:79], v[68:71], v[110:113], 0
	v_add_f32_e32 v177, v249, v177
	v_add_f32_e32 v177, v250, v177
	v_add_f32_e32 v177, v251, v177
	v_exp_f32_e32 v128, v128
	v_add_f32_e32 v177, v206, v177
	v_exp_f32_e32 v129, v129
	v_add_f32_e32 v177, v207, v177
	s_waitcnt lgkmcnt(1)
	v_mfma_f32_32x32x16_bf16 v[80:95], v[178:181], v[106:109], v[80:95]
	v_exp_f32_e32 v126, v126
	v_add_f32_e32 v177, v208, v177
	v_exp_f32_e32 v127, v127
	v_add_f32_e32 v177, v209, v177
	v_exp_f32_e32 v122, v122
	v_add_f32_e32 v177, v128, v177
	v_exp_f32_e32 v123, v123
	s_waitcnt lgkmcnt(0)
	v_mfma_f32_32x32x16_bf16 v[64:79], v[220:223], v[106:109], v[64:79]
	ds_read_b128 v[178:181], v173 offset:49152
	ds_read_b128 v[220:223], v173 offset:57344
	v_add_f32_e32 v177, v129, v177
	v_exp_f32_e32 v118, v118
	v_add_f32_e32 v177, v126, v177
	v_exp_f32_e32 v119, v119
	v_add_f32_e32 v177, v127, v177
	v_exp_f32_e32 v116, v116
	s_waitcnt lgkmcnt(1)
	v_mfma_f32_32x32x16_bf16 v[80:95], v[178:181], v[102:105], v[80:95]
	v_add_f32_e32 v177, v122, v177
	v_exp_f32_e32 v117, v117
	v_add_f32_e32 v177, v123, v177
	v_exp_f32_e32 v124, v124
	v_add_f32_e32 v177, v118, v177
	v_exp_f32_e32 v125, v125
	v_add_f32_e32 v177, v119, v177
	s_waitcnt lgkmcnt(0)
	v_mfma_f32_32x32x16_bf16 v[64:79], v[220:223], v[102:105], v[64:79]
	ds_read_b128 v[178:181], v172 offset:49152
	ds_read_b128 v[220:223], v172 offset:57344
	v_exp_f32_e32 v120, v120
	v_add_f32_e32 v177, v116, v177
	v_exp_f32_e32 v121, v121
	v_add_f32_e32 v177, v117, v177
	v_exp_f32_e32 v114, v114
	v_add_f32_e32 v177, v124, v177
	s_waitcnt lgkmcnt(1)
	v_mfma_f32_32x32x16_bf16 v[80:95], v[178:181], v[98:101], v[80:95]
	v_exp_f32_e32 v115, v115
	v_add_f32_e32 v177, v125, v177
	v_add_f32_e32 v177, v120, v177
	v_add_f32_e32 v177, v121, v177
	v_add_f32_e32 v177, v114, v177
	v_add_f32_e32 v177, v115, v177
	v_mov_b32_e32 v178, v177
	s_waitcnt lgkmcnt(0)
	v_mfma_f32_32x32x16_bf16 v[64:79], v[220:223], v[98:101], v[64:79]
	v_cvt_pk_bf16_f32 v212, v240, v241
	v_cvt_pk_bf16_f32 v213, v242, v243
	v_cvt_pk_bf16_f32 v214, v244, v245
	v_cvt_pk_bf16_f32 v215, v246, v247
	v_cvt_pk_bf16_f32 v180, v248, v249
	v_cvt_pk_bf16_f32 v181, v250, v251
	v_cvt_pk_bf16_f32 v182, v206, v207
	v_permlane32_swap_b32_e32 v177, v178
	v_cvt_pk_bf16_f32 v183, v208, v209
	v_permlane32_swap_b32_e32 v180, v182
	v_cvt_pk_bf16_f32 v184, v128, v129
	v_cvt_pk_bf16_f32 v185, v126, v127
	v_cvt_pk_bf16_f32 v186, v122, v123
	v_cvt_pk_bf16_f32 v187, v118, v119
	v_cvt_pk_bf16_f32 v216, v116, v117
	v_cvt_pk_bf16_f32 v217, v124, v125
	v_cvt_pk_bf16_f32 v218, v120, v121
	v_cvt_pk_bf16_f32 v219, v114, v115
	v_permlane32_swap_b32_e32 v212, v214
	v_permlane32_swap_b32_e32 v213, v215
	v_permlane32_swap_b32_e32 v181, v183
	v_permlane32_swap_b32_e32 v184, v186
	v_permlane32_swap_b32_e32 v185, v187
	v_permlane32_swap_b32_e32 v216, v218
	v_permlane32_swap_b32_e32 v217, v219
	v_add_u32_e32 v122, 0x10000, v176
	global_load_dwordx4 v[240:243], v176, s[58:59]
	global_load_dwordx4 v[244:247], v176, s[28:29]
	global_load_dwordx4 v[206:209], v122, s[58:59]
	s_nop 0
	global_load_dwordx4 v[248:251], v122, s[28:29]
	ds_read_b64_tr_b16 v[220:221], v160 offset:0
	ds_read_b64_tr_b16 v[222:223], v160 offset:0x800
	ds_read_b64_tr_b16 v[224:225], v160 offset:0x1000
	ds_read_b64_tr_b16 v[226:227], v160 offset:0x1800
	ds_read_b64_tr_b16 v[228:229], v160 offset:0x2000
	ds_read_b64_tr_b16 v[230:231], v160 offset:0x2800
	ds_read_b64_tr_b16 v[232:233], v160 offset:0x3000
	ds_read_b64_tr_b16 v[234:235], v160 offset:0x3800
	s_waitcnt lgkmcnt(0)
	s_nop 0
	v_mfma_f32_32x32x16_bf16 v[48:63], v[212:215], v[220:223], v[48:63]
	ds_read_b64_tr_b16 v[220:221], v160 offset:0x200
	ds_read_b64_tr_b16 v[222:223], v160 offset:0xa00
	v_max_f32_e32 v179, v81, v81
	v_max_f32_e32 v255, v80, v80
	v_max_f32_e32 v179, v255, v179
	v_max3_f32 v179, v179, v82, v83
	v_max3_f32 v179, v179, v84, v85
	v_mfma_f32_32x32x16_bf16 v[48:63], v[180:183], v[224:227], v[48:63]
	ds_read_b64_tr_b16 v[224:225], v160 offset:0x1200
	ds_read_b64_tr_b16 v[226:227], v160 offset:0x1a00
	v_max3_f32 v179, v179, v86, v87
	v_max3_f32 v179, v179, v88, v89
	v_max3_f32 v179, v179, v90, v91
	v_max3_f32 v179, v179, v92, v93
	v_max3_f32 v179, v179, v94, v95
	v_mfma_f32_32x32x16_bf16 v[48:63], v[184:187], v[228:231], v[48:63]
	ds_read_b64_tr_b16 v[228:229], v160 offset:0x2200
	ds_read_b64_tr_b16 v[230:231], v160 offset:0x2a00
	v_max3_f32 v179, v179, v64, v65
	v_max3_f32 v179, v179, v66, v67
	v_max3_f32 v179, v179, v68, v69
	v_max3_f32 v179, v179, v70, v71
	v_max3_f32 v179, v179, v72, v73
	v_mfma_f32_32x32x16_bf16 v[48:63], v[216:219], v[232:235], v[48:63]
	ds_read_b64_tr_b16 v[232:233], v160 offset:0x3200
	ds_read_b64_tr_b16 v[234:235], v160 offset:0x3a00
	v_max3_f32 v179, v179, v74, v75
	v_max3_f32 v179, v179, v76, v77
	v_max3_f32 v179, v179, v78, v79
	v_mov_b32_e32 v255, v179
	s_nop 1
	v_permlane32_swap_b32_e32 v179, v255
	s_waitcnt lgkmcnt(0)
; #define SBAR() __builtin_amdgcn_sched_barrier(0)
; #define SWRITE(b, i) do { *(bf16x8*)(V_lds + (b) * SHM_V + vst0) = sr_[i].vs0;          \
;     *(bf16x8*)(V_lds + (b) * SHM_V + vst1) = sr_[i].vs1; int kc = sc * 2;               \
;     *(bf16x8*)(K_lds + (b) * SHM_K + KSWZ(sr, kc)) = sr_[i].ks0;                       \
;     *(bf16x8*)(K_lds + (b) * SHM_K + KSWZ(32 + sr, kc)) = sr_[i].ks1; } while (0)
; #define SWAIT() asm volatile("s_waitcnt vmcnt(0)" ::: "memory")
; #define RESC(a) do { if (__any((a) < 1.f)) { if (hi == 0) al_l[r32] = (a); asm volatile("s_waitcnt lgkmcnt(0)" ::: "memory"); \
;     _Pragma("unroll") for (int d = 0; d < 4; ++d) _Pragma("unroll") for (int r = 0; r < 16; ++r) o[d][r] *= al_l[crow(r, hi)]; } } while (0)
; __device__ __forceinline__ void partialSM(f32x16& p0, f32x16& p1, float& m_reg, float& mn, float& alpha) {
;     constexpr float C = SCALE * 1.4426950408889634f;
;     float pmax = p0[0];
; #pragma unroll
;     for (int r = 1; r < 16; ++r) pmax = fmaxf(pmax, p0[r]);
; #pragma unroll
;     for (int r = 0; r < 16; ++r) pmax = fmaxf(pmax, p1[r]);
;     { auto rr = __builtin_amdgcn_permlane32_swap(__float_as_uint(pmax), __float_as_uint(pmax), false, false);
;       pmax = fmaxf(__uint_as_float(rr[0]), __uint_as_float(rr[1])); }
;     if (__builtin_expect(__all(pmax - m_reg <= THR / SCALE), 1)) { mn = m_reg; alpha = 1.f; }
;     else { mn = fmaxf(m_reg, pmax); alpha = __builtin_amdgcn_exp2f((m_reg - mn) * C); m_reg = mn; }
;     const float mnC = -mn * C;
; #pragma unroll
;     for (int r = 0; r < 16; ++r) p0[r] = fmaf(p0[r], C, mnC);
; #pragma unroll
;     for (int r = 0; r < 16; ++r) p1[r] = fmaf(p1[r], C, mnC);
; #pragma unroll
;     for (int r = 0; r < 16; ++r) p0[r] = __builtin_amdgcn_exp2f(p0[r]);
; }
; __device__ __forceinline__ void attn_unit(const bf16_t* Qb, const bf16_t* Kh, const bf16_t* Vh, bf16_t* Ob, float* scr, int seq, float lam, float onemli, const float* subg, char* lds) {
;     ...
;             SLOAD(SO, (j + 1) * KVBLK); SBAR();
;             pv_d0(o, vb0, pa0, pa1, pa2, pa3); partialSM(pB0, pB1, m_reg, mnB, alB);
;             __syncthreads(); SWAIT(); SWRITE(0, SE);
;             RESC(alB); __syncthreads();
	v_mfma_f32_32x32x16_bf16 v[32:47], v[212:215], v[220:223], v[32:47]
	ds_read_b64_tr_b16 v[220:221], v160 offset:0x400
	ds_read_b64_tr_b16 v[222:223], v160 offset:0xc00
	v_max_f32_e32 v255, v255, v255
	v_max_f32_e32 v179, v179, v179
	v_max_f32_e32 v179, v179, v255
	v_sub_f32_e32 v255, v179, v175
	v_cmp_ge_f32_e32 vcc, s65, v255
	v_mfma_f32_32x32x16_bf16 v[32:47], v[180:183], v[224:227], v[32:47]
	ds_read_b64_tr_b16 v[224:225], v160 offset:0x1400
	ds_read_b64_tr_b16 v[226:227], v160 offset:0x1c00
	v_max_f32_e32 v255, v175, v175
	v_max_f32_e32 v179, v255, v179
	v_sub_f32_e32 v255, v175, v179
	v_mul_f32_e32 v255, 0x3e38aa3b, v255
	v_exp_f32_e32 v255, v255
	v_mfma_f32_32x32x16_bf16 v[32:47], v[184:187], v[228:231], v[32:47]
	ds_read_b64_tr_b16 v[228:229], v160 offset:0x2400
	ds_read_b64_tr_b16 v[230:231], v160 offset:0x2c00
	s_cmp_eq_u64 vcc, exec
	s_cselect_b64 s[8:9], -1, 0
	v_cndmask_b32_e64 v255, v255, 1.0, s[8:9]
	v_cndmask_b32_e64 v175, v179, v175, s[8:9]
	v_mul_f32_e32 v179, 0xbe38aa3b, v175
	v_mfma_f32_32x32x16_bf16 v[32:47], v[216:219], v[232:235], v[32:47]
	ds_read_b64_tr_b16 v[232:233], v160 offset:0x3400
	ds_read_b64_tr_b16 v[234:235], v160 offset:0x3c00
	v_fmamk_f32 v80, v80, 0x3e38aa3b, v179
	v_fmamk_f32 v81, v81, 0x3e38aa3b, v179
	v_fmamk_f32 v82, v82, 0x3e38aa3b, v179
	v_fmamk_f32 v83, v83, 0x3e38aa3b, v179
	v_fmamk_f32 v84, v84, 0x3e38aa3b, v179
	s_waitcnt lgkmcnt(0)
	v_mfma_f32_32x32x16_bf16 v[16:31], v[212:215], v[220:223], v[16:31]
	ds_read_b64_tr_b16 v[220:221], v160 offset:0x600
	ds_read_b64_tr_b16 v[222:223], v160 offset:0xe00
	v_fmamk_f32 v85, v85, 0x3e38aa3b, v179
	v_fmamk_f32 v86, v86, 0x3e38aa3b, v179
	v_fmamk_f32 v87, v87, 0x3e38aa3b, v179
	v_fmamk_f32 v88, v88, 0x3e38aa3b, v179
	v_fmamk_f32 v89, v89, 0x3e38aa3b, v179
	v_mfma_f32_32x32x16_bf16 v[16:31], v[180:183], v[224:227], v[16:31]
	ds_read_b64_tr_b16 v[224:225], v160 offset:0x1600
	ds_read_b64_tr_b16 v[226:227], v160 offset:0x1e00
	v_fmamk_f32 v90, v90, 0x3e38aa3b, v179
	v_fmamk_f32 v91, v91, 0x3e38aa3b, v179
	v_fmamk_f32 v92, v92, 0x3e38aa3b, v179
	v_fmamk_f32 v93, v93, 0x3e38aa3b, v179
	v_fmamk_f32 v94, v94, 0x3e38aa3b, v179
	v_mfma_f32_32x32x16_bf16 v[16:31], v[184:187], v[228:231], v[16:31]
	ds_read_b64_tr_b16 v[228:229], v160 offset:0x2600
	ds_read_b64_tr_b16 v[230:231], v160 offset:0x2e00
	v_fmamk_f32 v95, v95, 0x3e38aa3b, v179
	v_exp_f32_e32 v127, v80
	v_exp_f32_e32 v129, v81
	v_mfma_f32_32x32x16_bf16 v[16:31], v[216:219], v[232:235], v[16:31]
	ds_read_b64_tr_b16 v[232:233], v160 offset:0x3600
	ds_read_b64_tr_b16 v[234:235], v160 offset:0x3e00
	v_exp_f32_e32 v125, v82
	v_exp_f32_e32 v128, v83
	v_exp_f32_e32 v123, v84
	s_waitcnt lgkmcnt(0)
	v_mfma_f32_32x32x16_bf16 v[0:15], v[212:215], v[220:223], v[0:15]
	s_barrier
	s_waitcnt vmcnt(0)
	s_waitcnt vmcnt(3)
	ds_write_b128 v163, v[240:243]
	s_waitcnt vmcnt(1)
	ds_write_b128 v164, v[206:209]
	ds_write_b128 v161, v[244:247] offset:32768
	s_waitcnt vmcnt(0)
	ds_write_b128 v162, v[248:251] offset:32768
	v_exp_f32_e32 v126, v85
	v_exp_f32_e32 v122, v86
	v_exp_f32_e32 v124, v87
	v_mfma_f32_32x32x16_bf16 v[0:15], v[180:183], v[224:227], v[0:15]
	v_exp_f32_e32 v119, v88
	v_exp_f32_e32 v121, v89
	v_exp_f32_e32 v117, v90
	v_mfma_f32_32x32x16_bf16 v[0:15], v[184:187], v[228:231], v[0:15]
	v_exp_f32_e32 v120, v91
	v_exp_f32_e32 v115, v92
	v_exp_f32_e32 v118, v93
	v_mfma_f32_32x32x16_bf16 v[0:15], v[216:219], v[232:235], v[0:15]
	v_exp_f32_e32 v114, v94
	v_exp_f32_e32 v116, v95
	v_mov_b32_e32 v180, v255
	v_cmp_gt_f32_e32 vcc, 1.0, v180
	s_cbranch_vccz .LBB0_266
	s_and_saveexec_b64 s[2:3], s[6:7]
	ds_write_b32 v157, v180 offset:128
	s_or_b64 exec, exec, s[2:3]
	s_waitcnt lgkmcnt(0)
	ds_read_b128 v[240:243], v158 offset:224
	ds_read_b128 v[244:247], v158 offset:192
	ds_read_b128 v[248:251], v158 offset:160
	ds_read_b128 v[206:209], v158 offset:128
	s_waitcnt lgkmcnt(3)
	v_pk_mul_f32 v[62:63], v[62:63], v[242:243]
	s_waitcnt lgkmcnt(2)
	v_pk_mul_f32 v[58:59], v[58:59], v[246:247]
	s_waitcnt lgkmcnt(1)
	v_pk_mul_f32 v[54:55], v[54:55], v[250:251]
	s_waitcnt lgkmcnt(0)
	v_pk_mul_f32 v[50:51], v[50:51], v[208:209]
	v_pk_mul_f32 v[60:61], v[60:61], v[240:241]
	v_pk_mul_f32 v[56:57], v[56:57], v[244:245]
	v_pk_mul_f32 v[52:53], v[52:53], v[248:249]
	v_pk_mul_f32 v[48:49], v[48:49], v[206:207]
	v_pk_mul_f32 v[46:47], v[46:47], v[242:243]
	v_pk_mul_f32 v[42:43], v[42:43], v[246:247]
	v_pk_mul_f32 v[38:39], v[38:39], v[250:251]
	v_pk_mul_f32 v[34:35], v[34:35], v[208:209]
	v_pk_mul_f32 v[44:45], v[44:45], v[240:241]
	v_pk_mul_f32 v[40:41], v[40:41], v[244:245]
	v_pk_mul_f32 v[36:37], v[36:37], v[248:249]
	v_pk_mul_f32 v[32:33], v[32:33], v[206:207]
	v_pk_mul_f32 v[30:31], v[30:31], v[242:243]
	v_pk_mul_f32 v[26:27], v[26:27], v[246:247]
	v_pk_mul_f32 v[22:23], v[22:23], v[250:251]
	v_pk_mul_f32 v[18:19], v[18:19], v[208:209]
	v_pk_mul_f32 v[28:29], v[28:29], v[240:241]
	v_pk_mul_f32 v[24:25], v[24:25], v[244:245]
	v_pk_mul_f32 v[20:21], v[20:21], v[248:249]
	v_pk_mul_f32 v[16:17], v[16:17], v[206:207]
	v_pk_mul_f32 v[14:15], v[14:15], v[242:243]
	v_pk_mul_f32 v[10:11], v[10:11], v[246:247]
	v_pk_mul_f32 v[6:7], v[6:7], v[250:251]
	v_pk_mul_f32 v[2:3], v[2:3], v[208:209]
	v_pk_mul_f32 v[12:13], v[12:13], v[240:241]
	v_pk_mul_f32 v[8:9], v[8:9], v[244:245]
	v_pk_mul_f32 v[4:5], v[4:5], v[248:249]
	v_pk_mul_f32 v[0:1], v[0:1], v[206:207]
; #define SBAR() __builtin_amdgcn_sched_barrier(0)
; #define RESC(a) do { if (__any((a) < 1.f)) { if (hi == 0) al_l[r32] = (a); asm volatile("s_waitcnt lgkmcnt(0)" ::: "memory"); \
;     _Pragma("unroll") for (int d = 0; d < 4; ++d) _Pragma("unroll") for (int r = 0; r < 16; ++r) o[d][r] *= al_l[crow(r, hi)]; } } while (0)
; __device__ __forceinline__ void finishSM(f32x16& p0, f32x16& p1, float alpha, float& l_reg, bf16x8& pa0, bf16x8& pa1, bf16x8& pa2, bf16x8& pa3) {
; #pragma unroll
;     for (int r = 0; r < 16; ++r) p1[r] = __builtin_amdgcn_exp2f(p1[r]);
;     float ps = 0;
; #pragma unroll
;     for (int r = 0; r < 16; ++r) ps += p0[r];
; #pragma unroll
;     for (int r = 0; r < 16; ++r) ps += p1[r];
;     { auto rr = __builtin_amdgcn_permlane32_swap(__float_as_uint(ps), __float_as_uint(ps), false, false);
;       ps = __uint_as_float(rr[0]) + __uint_as_float(rr[1]); }
;     l_reg = l_reg * alpha + ps;
;     ...
;     PK4(p0, 0, pa0); PK4(p0, 8, pa1); PK4(p1, 0, pa2); PK4(p1, 8, pa3);
;     ...
; }
; __device__ __forceinline__ void attn_unit(const bf16_t* Qb, const bf16_t* Kh, const bf16_t* Vh, bf16_t* Ob, float* scr, int seq, float lam, float onemli, const float* subg, char* lds) {
;     ...
;             RESC(alB); __syncthreads();
;             SBAR(); qkt(pA0, pA1, K_lds, qr, r32, hi, comp);
;             finishSM(pB0, pB1, alB, l_reg, pa0, pa1, pa2, pa3); SBAR();
;             SLOAD(SE, (j + 2) * KVBLK); SBAR();
;             pv_d0(o, vb0 + (int)SHM_V, pa0, pa1, pa2, pa3); partialSM(pA0, pA1, m_reg, mnA, alA);
.LBB0_266:
	v_fmamk_f32 v189, v64, 0x3e38aa3b, v179
	v_fmamk_f32 v211, v65, 0x3e38aa3b, v179
	v_fmamk_f32 v212, v66, 0x3e38aa3b, v179
	v_fmamk_f32 v213, v67, 0x3e38aa3b, v179
	v_fmamk_f32 v214, v68, 0x3e38aa3b, v179
	v_fmamk_f32 v182, v69, 0x3e38aa3b, v179
	v_fmamk_f32 v183, v70, 0x3e38aa3b, v179
	v_fmamk_f32 v184, v71, 0x3e38aa3b, v179
	v_fmamk_f32 v185, v72, 0x3e38aa3b, v179
	v_fmamk_f32 v186, v73, 0x3e38aa3b, v179
	v_fmamk_f32 v187, v74, 0x3e38aa3b, v179
	v_fmamk_f32 v188, v75, 0x3e38aa3b, v179
	v_fmamk_f32 v181, v76, 0x3e38aa3b, v179
	v_fmamk_f32 v215, v77, 0x3e38aa3b, v179
	v_fmamk_f32 v216, v78, 0x3e38aa3b, v179
	v_fmac_f32_e32 v179, 0x3e38aa3b, v79
	s_waitcnt lgkmcnt(0)
	s_barrier
	ds_read_b128 v[64:67], v170 offset:32768
	ds_read_b128 v[68:71], v170 offset:40960
	v_exp_f32_e32 v203, v181
	v_add_f32_e32 v181, 0, v127
	v_add_f32_e32 v181, v129, v181
	s_waitcnt lgkmcnt(1)
	v_mfma_f32_32x32x16_bf16 v[80:95], v[64:67], v[110:113], 0
	v_add_f32_e32 v181, v125, v181
	v_add_f32_e32 v181, v128, v181
	v_add_f32_e32 v181, v123, v181
	ds_read_b128 v[218:221], v171 offset:32768
	ds_read_b128 v[222:225], v171 offset:40960
	v_add_f32_e32 v181, v126, v181
	v_add_f32_e32 v181, v122, v181
	v_add_f32_e32 v181, v124, v181
	s_waitcnt lgkmcnt(2)
	v_mfma_f32_32x32x16_bf16 v[64:79], v[68:71], v[110:113], 0
	v_add_f32_e32 v181, v119, v181
	v_add_f32_e32 v181, v121, v181
	v_add_f32_e32 v181, v117, v181
	v_add_f32_e32 v181, v120, v181
	v_exp_f32_e32 v189, v189
	v_add_f32_e32 v181, v115, v181
	v_exp_f32_e32 v190, v211
	s_waitcnt lgkmcnt(1)
	v_mfma_f32_32x32x16_bf16 v[80:95], v[218:221], v[106:109], v[80:95]
	v_add_f32_e32 v181, v118, v181
	v_exp_f32_e32 v191, v212
	v_add_f32_e32 v181, v114, v181
	v_exp_f32_e32 v192, v213
	v_add_f32_e32 v181, v116, v181
	v_exp_f32_e32 v193, v214
	v_add_f32_e32 v181, v189, v181
	s_waitcnt lgkmcnt(0)
	v_mfma_f32_32x32x16_bf16 v[64:79], v[222:225], v[106:109], v[64:79]
	ds_read_b128 v[218:221], v173 offset:32768
	ds_read_b128 v[222:225], v173 offset:40960
	v_exp_f32_e32 v194, v182
	v_add_f32_e32 v181, v190, v181
	v_exp_f32_e32 v183, v183
	v_add_f32_e32 v181, v191, v181
	v_exp_f32_e32 v195, v184
	v_add_f32_e32 v181, v192, v181
	s_waitcnt lgkmcnt(1)
	v_mfma_f32_32x32x16_bf16 v[80:95], v[218:221], v[102:105], v[80:95]
	v_exp_f32_e32 v200, v185
	v_add_f32_e32 v181, v193, v181
	v_exp_f32_e32 v201, v186
	v_add_f32_e32 v181, v194, v181
	v_exp_f32_e32 v202, v187
	v_add_f32_e32 v181, v183, v181
	v_exp_f32_e32 v188, v188
	s_waitcnt lgkmcnt(0)
	v_mfma_f32_32x32x16_bf16 v[64:79], v[222:225], v[102:105], v[64:79]
	ds_read_b128 v[218:221], v172 offset:32768
	ds_read_b128 v[222:225], v172 offset:40960
	v_add_f32_e32 v181, v195, v181
	v_add_f32_e32 v181, v200, v181
	v_exp_f32_e32 v204, v215
	v_add_f32_e32 v181, v201, v181
	v_exp_f32_e32 v205, v216
	v_add_f32_e32 v181, v202, v181
	s_waitcnt lgkmcnt(1)
	v_mfma_f32_32x32x16_bf16 v[80:95], v[218:221], v[98:101], v[80:95]
	v_exp_f32_e32 v179, v179
	v_add_f32_e32 v181, v188, v181
	v_add_f32_e32 v181, v203, v181
	v_add_f32_e32 v181, v204, v181
	v_add_f32_e32 v181, v205, v181
	v_add_f32_e32 v181, v179, v181
	v_mov_b32_e32 v182, v181
	s_waitcnt lgkmcnt(0)
	v_mfma_f32_32x32x16_bf16 v[64:79], v[222:225], v[98:101], v[64:79]
	v_permlane32_swap_b32_e32 v181, v182
	v_cvt_pk_bf16_f32 v184, v127, v129
	v_cvt_pk_bf16_f32 v185, v125, v128
	v_cvt_pk_bf16_f32 v186, v123, v126
	v_cvt_pk_bf16_f32 v187, v122, v124
	v_cvt_pk_bf16_f32 v212, v119, v121
	v_cvt_pk_bf16_f32 v213, v117, v120
	v_cvt_pk_bf16_f32 v214, v115, v118
	v_cvt_pk_bf16_f32 v215, v114, v116
	v_cvt_pk_bf16_f32 v216, v189, v190
	v_cvt_pk_bf16_f32 v217, v191, v192
	v_cvt_pk_bf16_f32 v218, v193, v194
	v_cvt_pk_bf16_f32 v219, v183, v195
	v_cvt_pk_bf16_f32 v220, v200, v201
	v_cvt_pk_bf16_f32 v221, v202, v188
	v_cvt_pk_bf16_f32 v222, v203, v204
	v_cvt_pk_bf16_f32 v223, v205, v179
	s_nop 0
	v_permlane32_swap_b32_e32 v184, v186
	v_permlane32_swap_b32_e32 v185, v187
	v_permlane32_swap_b32_e32 v212, v214
	v_permlane32_swap_b32_e32 v213, v215
	v_permlane32_swap_b32_e32 v216, v218
	v_permlane32_swap_b32_e32 v217, v219
	v_permlane32_swap_b32_e32 v220, v222
	v_permlane32_swap_b32_e32 v221, v223
	v_add_u32_e32 v118, 0x20000, v176
	v_add_u32_e32 v122, 0x30000, v176
	global_load_dwordx4 v[114:117], v118, s[58:59]
	s_nop 0
	global_load_dwordx4 v[118:121], v118, s[28:29]
	s_nop 0
	global_load_dwordx4 v[126:129], v122, s[58:59]
	s_nop 0
	global_load_dwordx4 v[122:125], v122, s[28:29]
	ds_read_b64_tr_b16 v[224:225], v159 offset:0
	ds_read_b64_tr_b16 v[226:227], v159 offset:0x800
	ds_read_b64_tr_b16 v[228:229], v159 offset:0x1000
	ds_read_b64_tr_b16 v[230:231], v159 offset:0x1800
	ds_read_b64_tr_b16 v[232:233], v159 offset:0x2000
	ds_read_b64_tr_b16 v[234:235], v159 offset:0x2800
	ds_read_b64_tr_b16 v[236:237], v159 offset:0x3000
	ds_read_b64_tr_b16 v[238:239], v159 offset:0x3800
	s_waitcnt lgkmcnt(0)
	s_nop 0
	v_mfma_f32_32x32x16_bf16 v[48:63], v[184:187], v[224:227], v[48:63]
	ds_read_b64_tr_b16 v[224:225], v159 offset:0x200
	ds_read_b64_tr_b16 v[226:227], v159 offset:0xa00
	v_max_f32_e32 v255, v81, v81
	v_max_f32_e32 v210, v80, v80
	v_max_f32_e32 v255, v210, v255
	v_max3_f32 v255, v255, v82, v83
	v_max3_f32 v255, v255, v84, v85
	v_mfma_f32_32x32x16_bf16 v[48:63], v[212:215], v[228:231], v[48:63]
	ds_read_b64_tr_b16 v[228:229], v159 offset:0x1200
	ds_read_b64_tr_b16 v[230:231], v159 offset:0x1a00
	v_max3_f32 v255, v255, v86, v87
	v_max3_f32 v255, v255, v88, v89
	v_max3_f32 v255, v255, v90, v91
	v_max3_f32 v255, v255, v92, v93
	v_max3_f32 v255, v255, v94, v95
	v_mfma_f32_32x32x16_bf16 v[48:63], v[216:219], v[232:235], v[48:63]
	ds_read_b64_tr_b16 v[232:233], v159 offset:0x2200
	ds_read_b64_tr_b16 v[234:235], v159 offset:0x2a00
	v_max3_f32 v255, v255, v64, v65
	v_max3_f32 v255, v255, v66, v67
	v_max3_f32 v255, v255, v68, v69
	v_max3_f32 v255, v255, v70, v71
	v_max3_f32 v255, v255, v72, v73
	v_mfma_f32_32x32x16_bf16 v[48:63], v[220:223], v[236:239], v[48:63]
	ds_read_b64_tr_b16 v[236:237], v159 offset:0x3200
	ds_read_b64_tr_b16 v[238:239], v159 offset:0x3a00
	v_max3_f32 v255, v255, v74, v75
	v_max3_f32 v255, v255, v76, v77
	v_max3_f32 v255, v255, v78, v79
	v_mov_b32_e32 v210, v255
	s_nop 1
	v_permlane32_swap_b32_e32 v255, v210
	s_waitcnt lgkmcnt(0)
; #define SWRITE(b, i) do { *(bf16x8*)(V_lds + (b) * SHM_V + vst0) = sr_[i].vs0;          \
;     *(bf16x8*)(V_lds + (b) * SHM_V + vst1) = sr_[i].vs1; int kc = sc * 2;               \
;     *(bf16x8*)(K_lds + (b) * SHM_K + KSWZ(sr, kc)) = sr_[i].ks0;                       \
;     *(bf16x8*)(K_lds + (b) * SHM_K + KSWZ(32 + sr, kc)) = sr_[i].ks1; } while (0)
; #define SWAIT() asm volatile("s_waitcnt vmcnt(0)" ::: "memory")
; #define RESC(a) do { if (__any((a) < 1.f)) { if (hi == 0) al_l[r32] = (a); asm volatile("s_waitcnt lgkmcnt(0)" ::: "memory"); \
;     _Pragma("unroll") for (int d = 0; d < 4; ++d) _Pragma("unroll") for (int r = 0; r < 16; ++r) o[d][r] *= al_l[crow(r, hi)]; } } while (0)
; __device__ __forceinline__ void partialSM(f32x16& p0, f32x16& p1, float& m_reg, float& mn, float& alpha) {
;     constexpr float C = SCALE * 1.4426950408889634f;
;     float pmax = p0[0];
; #pragma unroll
;     for (int r = 1; r < 16; ++r) pmax = fmaxf(pmax, p0[r]);
; #pragma unroll
;     for (int r = 0; r < 16; ++r) pmax = fmaxf(pmax, p1[r]);
;     { auto rr = __builtin_amdgcn_permlane32_swap(__float_as_uint(pmax), __float_as_uint(pmax), false, false);
;       pmax = fmaxf(__uint_as_float(rr[0]), __uint_as_float(rr[1])); }
;     if (__builtin_expect(__all(pmax - m_reg <= THR / SCALE), 1)) { mn = m_reg; alpha = 1.f; }
;     else { mn = fmaxf(m_reg, pmax); alpha = __builtin_amdgcn_exp2f((m_reg - mn) * C); m_reg = mn; }
;     const float mnC = -mn * C;
; #pragma unroll
;     for (int r = 0; r < 16; ++r) p0[r] = fmaf(p0[r], C, mnC);
; #pragma unroll
;     for (int r = 0; r < 16; ++r) p1[r] = fmaf(p1[r], C, mnC);
; #pragma unroll
;     for (int r = 0; r < 16; ++r) p0[r] = __builtin_amdgcn_exp2f(p0[r]);
; }
; __device__ __forceinline__ void attn_unit(const bf16_t* Qb, const bf16_t* Kh, const bf16_t* Vh, bf16_t* Ob, float* scr, int seq, float lam, float onemli, const float* subg, char* lds) {
;     ...
;             pv_d0(o, vb0 + (int)SHM_V, pa0, pa1, pa2, pa3); partialSM(pA0, pA1, m_reg, mnA, alA);
;             __syncthreads(); SWAIT(); SWRITE(1, SO);
;             RESC(alA); __syncthreads();
	v_mfma_f32_32x32x16_bf16 v[32:47], v[184:187], v[224:227], v[32:47]
	ds_read_b64_tr_b16 v[224:225], v159 offset:0x400
	ds_read_b64_tr_b16 v[226:227], v159 offset:0xc00
	v_max_f32_e32 v210, v210, v210
	v_max_f32_e32 v255, v255, v255
	v_max_f32_e32 v255, v255, v210
	v_sub_f32_e32 v210, v255, v175
	v_cmp_ge_f32_e32 vcc, s65, v210
	v_mfma_f32_32x32x16_bf16 v[32:47], v[212:215], v[228:231], v[32:47]
	ds_read_b64_tr_b16 v[228:229], v159 offset:0x1400
	ds_read_b64_tr_b16 v[230:231], v159 offset:0x1c00
	v_max_f32_e32 v210, v175, v175
	v_max_f32_e32 v210, v210, v255
	v_sub_f32_e32 v255, v175, v210
	v_mul_f32_e32 v255, 0x3e38aa3b, v255
	v_exp_f32_e32 v255, v255
	v_mfma_f32_32x32x16_bf16 v[32:47], v[216:219], v[232:235], v[32:47]
	ds_read_b64_tr_b16 v[232:233], v159 offset:0x2400
	ds_read_b64_tr_b16 v[234:235], v159 offset:0x2c00
	s_cmp_eq_u64 vcc, exec
	s_cselect_b64 s[8:9], -1, 0
	v_cndmask_b32_e64 v255, v255, 1.0, s[8:9]
	v_cndmask_b32_e64 v175, v210, v175, s[8:9]
	v_mul_f32_e32 v210, 0xbe38aa3b, v175
	v_mfma_f32_32x32x16_bf16 v[32:47], v[220:223], v[236:239], v[32:47]
	ds_read_b64_tr_b16 v[236:237], v159 offset:0x3400
	ds_read_b64_tr_b16 v[238:239], v159 offset:0x3c00
	v_fmamk_f32 v80, v80, 0x3e38aa3b, v210
	v_fmamk_f32 v81, v81, 0x3e38aa3b, v210
	v_fmamk_f32 v82, v82, 0x3e38aa3b, v210
	v_fmamk_f32 v83, v83, 0x3e38aa3b, v210
	v_fmamk_f32 v84, v84, 0x3e38aa3b, v210
	s_waitcnt lgkmcnt(0)
	v_mfma_f32_32x32x16_bf16 v[16:31], v[184:187], v[224:227], v[16:31]
	ds_read_b64_tr_b16 v[224:225], v159 offset:0x600
	ds_read_b64_tr_b16 v[226:227], v159 offset:0xe00
	v_fmamk_f32 v85, v85, 0x3e38aa3b, v210
	v_fmamk_f32 v86, v86, 0x3e38aa3b, v210
	v_fmamk_f32 v87, v87, 0x3e38aa3b, v210
	v_fmamk_f32 v88, v88, 0x3e38aa3b, v210
	v_fmamk_f32 v89, v89, 0x3e38aa3b, v210
	v_mfma_f32_32x32x16_bf16 v[16:31], v[212:215], v[228:231], v[16:31]
	ds_read_b64_tr_b16 v[228:229], v159 offset:0x1600
	ds_read_b64_tr_b16 v[230:231], v159 offset:0x1e00
	v_fmamk_f32 v90, v90, 0x3e38aa3b, v210
	v_fmamk_f32 v91, v91, 0x3e38aa3b, v210
	v_fmamk_f32 v92, v92, 0x3e38aa3b, v210
	v_fmamk_f32 v93, v93, 0x3e38aa3b, v210
	v_fmamk_f32 v94, v94, 0x3e38aa3b, v210
	v_mfma_f32_32x32x16_bf16 v[16:31], v[216:219], v[232:235], v[16:31]
	ds_read_b64_tr_b16 v[232:233], v159 offset:0x2600
	ds_read_b64_tr_b16 v[234:235], v159 offset:0x2e00
	v_fmamk_f32 v95, v95, 0x3e38aa3b, v210
	v_exp_f32_e32 v240, v80
	v_exp_f32_e32 v241, v81
	v_mfma_f32_32x32x16_bf16 v[16:31], v[220:223], v[236:239], v[16:31]
	ds_read_b64_tr_b16 v[236:237], v159 offset:0x3600
	ds_read_b64_tr_b16 v[238:239], v159 offset:0x3e00
	v_exp_f32_e32 v242, v82
	v_exp_f32_e32 v243, v83
	v_exp_f32_e32 v244, v84
	s_waitcnt lgkmcnt(0)
	v_mfma_f32_32x32x16_bf16 v[0:15], v[184:187], v[224:227], v[0:15]
	s_barrier
	s_waitcnt vmcnt(0)
	s_waitcnt vmcnt(3)
	ds_write_b128 v163, v[114:117] offset:16384
	s_waitcnt vmcnt(1)
	ds_write_b128 v164, v[126:129] offset:16384
	ds_write_b128 v161, v[118:121] offset:49152
	s_waitcnt vmcnt(0)
	ds_write_b128 v162, v[122:125] offset:49152
	v_exp_f32_e32 v245, v85
	v_exp_f32_e32 v246, v86
	v_exp_f32_e32 v247, v87
	v_mfma_f32_32x32x16_bf16 v[0:15], v[212:215], v[228:231], v[0:15]
	v_exp_f32_e32 v248, v88
	v_exp_f32_e32 v249, v89
	v_exp_f32_e32 v250, v90
	v_mfma_f32_32x32x16_bf16 v[0:15], v[216:219], v[232:235], v[0:15]
	v_exp_f32_e32 v251, v91
	v_exp_f32_e32 v206, v92
	v_exp_f32_e32 v207, v93
	v_mfma_f32_32x32x16_bf16 v[0:15], v[220:223], v[236:239], v[0:15]
	v_exp_f32_e32 v208, v94
	v_exp_f32_e32 v209, v95
	v_mov_b32_e32 v179, v255
	v_cmp_gt_f32_e32 vcc, 1.0, v179
	s_cbranch_vccz .LBB0_270
	s_and_saveexec_b64 s[2:3], s[6:7]
	ds_write_b32 v157, v179 offset:128
	s_or_b64 exec, exec, s[2:3]
	s_waitcnt lgkmcnt(0)
	ds_read_b128 v[114:117], v158 offset:224
	ds_read_b128 v[118:121], v158 offset:192
	ds_read_b128 v[122:125], v158 offset:160
	ds_read_b128 v[126:129], v158 offset:128
	s_waitcnt lgkmcnt(3)
	v_pk_mul_f32 v[62:63], v[62:63], v[116:117]
	s_waitcnt lgkmcnt(2)
	v_pk_mul_f32 v[58:59], v[58:59], v[120:121]
	s_waitcnt lgkmcnt(1)
	v_pk_mul_f32 v[54:55], v[54:55], v[124:125]
	s_waitcnt lgkmcnt(0)
	v_pk_mul_f32 v[50:51], v[50:51], v[128:129]
	v_pk_mul_f32 v[60:61], v[60:61], v[114:115]
	v_pk_mul_f32 v[56:57], v[56:57], v[118:119]
	v_pk_mul_f32 v[52:53], v[52:53], v[122:123]
	v_pk_mul_f32 v[48:49], v[48:49], v[126:127]
	v_pk_mul_f32 v[46:47], v[46:47], v[116:117]
	v_pk_mul_f32 v[42:43], v[42:43], v[120:121]
	v_pk_mul_f32 v[38:39], v[38:39], v[124:125]
	v_pk_mul_f32 v[34:35], v[34:35], v[128:129]
	v_pk_mul_f32 v[44:45], v[44:45], v[114:115]
	v_pk_mul_f32 v[40:41], v[40:41], v[118:119]
	v_pk_mul_f32 v[36:37], v[36:37], v[122:123]
	v_pk_mul_f32 v[32:33], v[32:33], v[126:127]
	v_pk_mul_f32 v[30:31], v[30:31], v[116:117]
	v_pk_mul_f32 v[26:27], v[26:27], v[120:121]
	v_pk_mul_f32 v[22:23], v[22:23], v[124:125]
	v_pk_mul_f32 v[18:19], v[18:19], v[128:129]
	v_pk_mul_f32 v[28:29], v[28:29], v[114:115]
	v_pk_mul_f32 v[24:25], v[24:25], v[118:119]
	v_pk_mul_f32 v[20:21], v[20:21], v[122:123]
	v_pk_mul_f32 v[16:17], v[16:17], v[126:127]
	v_pk_mul_f32 v[14:15], v[14:15], v[116:117]
	v_pk_mul_f32 v[10:11], v[10:11], v[120:121]
	v_pk_mul_f32 v[6:7], v[6:7], v[124:125]
	v_pk_mul_f32 v[2:3], v[2:3], v[128:129]
	v_pk_mul_f32 v[12:13], v[12:13], v[114:115]
	v_pk_mul_f32 v[8:9], v[8:9], v[118:119]
	v_pk_mul_f32 v[4:5], v[4:5], v[122:123]
	v_pk_mul_f32 v[0:1], v[0:1], v[126:127]
; #define SBAR() __builtin_amdgcn_sched_barrier(0)
; #define RESC(a) do { if (__any((a) < 1.f)) { if (hi == 0) al_l[r32] = (a); asm volatile("s_waitcnt lgkmcnt(0)" ::: "memory"); \
;     _Pragma("unroll") for (int d = 0; d < 4; ++d) _Pragma("unroll") for (int r = 0; r < 16; ++r) o[d][r] *= al_l[crow(r, hi)]; } } while (0)
; __device__ __forceinline__ void partialSM(f32x16& p0, f32x16& p1, float& m_reg, float& mn, float& alpha) {
;     ...
; #pragma unroll
;     for (int r = 0; r < 16; ++r) p0[r] = fmaf(p0[r], C, mnC);
; #pragma unroll
;     for (int r = 0; r < 16; ++r) p1[r] = fmaf(p1[r], C, mnC);
; #pragma unroll
;     for (int r = 0; r < 16; ++r) p0[r] = __builtin_amdgcn_exp2f(p0[r]);
; }
; __device__ __forceinline__ void finishSM(f32x16& p0, f32x16& p1, float alpha, float& l_reg, bf16x8& pa0, bf16x8& pa1, bf16x8& pa2, bf16x8& pa3) {
; #pragma unroll
;     for (int r = 0; r < 16; ++r) p1[r] = __builtin_amdgcn_exp2f(p1[r]);
;     float ps = 0;
; #pragma unroll
;     for (int r = 0; r < 16; ++r) ps += p0[r];
; #pragma unroll
;     for (int r = 0; r < 16; ++r) ps += p1[r];
;     { auto rr = __builtin_amdgcn_permlane32_swap(__float_as_uint(ps), __float_as_uint(ps), false, false);
;       ps = __uint_as_float(rr[0]) + __uint_as_float(rr[1]); }
;     l_reg = l_reg * alpha + ps;
; __device__ __forceinline__ void attn_unit(const bf16_t* Qb, const bf16_t* Kh, const bf16_t* Vh, bf16_t* Ob, float* scr, int seq, float lam, float onemli, const float* subg, char* lds) {
;     ...
;             RESC(alA); __syncthreads();
;         }
;         SBAR(); qkt(pB0, pB1, K_lds + SHM_K, qr, r32, hi, comp);
;         finishSM(pA0, pA1, alA, l_reg, pa0, pa1, pa2, pa3); SBAR();
;         pv_d0(o, vb0, pa0, pa1, pa2, pa3); partialSM(pB0, pB1, m_reg, mnB, alB);
.LBB0_270:
	v_mov_b32_e32 v114, v210
	v_pk_fma_f32 v[128:129], v[64:65], s[72:73], v[114:115] op_sel_hi:[1,0,0]
	v_add_f32_e32 v64, v177, v178
	v_fmac_f32_e32 v64, v174, v169
	v_add_f32_e32 v169, v181, v182
	s_add_i32 s76, s76, 2
	v_pk_fma_f32 v[126:127], v[66:67], s[72:73], v[114:115] op_sel_hi:[1,0,0]
	v_pk_fma_f32 v[122:123], v[68:69], s[72:73], v[114:115] op_sel_hi:[1,0,0]
	v_pk_fma_f32 v[118:119], v[70:71], s[72:73], v[114:115] op_sel_hi:[1,0,0]
	v_pk_fma_f32 v[116:117], v[72:73], s[72:73], v[114:115] op_sel_hi:[1,0,0]
	v_pk_fma_f32 v[124:125], v[74:75], s[72:73], v[114:115] op_sel_hi:[1,0,0]
	v_pk_fma_f32 v[120:121], v[76:77], s[72:73], v[114:115] op_sel_hi:[1,0,0]
	v_pk_fma_f32 v[114:115], v[78:79], s[72:73], v[114:115] op_sel_hi:[1,0,0]
	v_fmac_f32_e32 v169, v64, v180
	s_cmp_ge_u32 s76, s67
	v_add_u32_e32 v176, 0x40000, v176
	s_waitcnt lgkmcnt(0)
	s_barrier
	s_cbranch_scc1 .LBB0_272
	v_mov_b32_e32 v174, v179
	s_branch .LBB0_262
.LBB0_272:
	v_mov_b32_e32 v212, v240
	v_mov_b32_e32 v216, v241
	v_mov_b32_e32 v213, v242
	v_mov_b32_e32 v217, v243
	v_mov_b32_e32 v214, v244
	v_mov_b32_e32 v218, v245
	v_mov_b32_e32 v215, v246
	v_mov_b32_e32 v219, v247
	v_mov_b32_e32 v183, v248
	v_mov_b32_e32 v187, v249
	v_mov_b32_e32 v184, v250
	v_mov_b32_e32 v188, v251
	v_mov_b32_e32 v185, v206
	v_mov_b32_e32 v189, v207
	v_mov_b32_e32 v186, v208
	v_mov_b32_e32 v211, v209
	ds_read_b128 v[64:67], v170 offset:49152
	ds_read_b128 v[68:71], v170 offset:57344
	v_exp_f32_e32 v118, v118
	v_exp_f32_e32 v119, v119
	v_exp_f32_e32 v116, v116
	s_waitcnt lgkmcnt(1)
	v_mfma_f32_32x32x16_bf16 v[80:95], v[64:67], v[110:113], 0
	v_exp_f32_e32 v117, v117
	v_exp_f32_e32 v120, v120
	v_exp_f32_e32 v121, v121
	v_exp_f32_e32 v115, v115
	s_waitcnt lgkmcnt(0)
	v_mfma_f32_32x32x16_bf16 v[64:79], v[68:71], v[110:113], 0
	ds_read_b128 v[110:113], v171 offset:49152
	ds_read_b128 v[220:223], v171 offset:57344
	s_waitcnt lgkmcnt(1)
	v_mfma_f32_32x32x16_bf16 v[80:95], v[110:113], v[106:109], v[80:95]
	s_waitcnt lgkmcnt(0)
	v_mfma_f32_32x32x16_bf16 v[64:79], v[220:223], v[106:109], v[64:79]
	ds_read_b128 v[106:109], v173 offset:49152
	ds_read_b128 v[110:113], v173 offset:57344
	s_waitcnt lgkmcnt(1)
	v_mfma_f32_32x32x16_bf16 v[80:95], v[106:109], v[102:105], v[80:95]
	s_waitcnt lgkmcnt(0)
	v_mfma_f32_32x32x16_bf16 v[64:79], v[110:113], v[102:105], v[64:79]
	ds_read_b128 v[102:105], v172 offset:49152
	ds_read_b128 v[106:109], v172 offset:57344
	v_exp_f32_e32 v110, v126
	v_exp_f32_e32 v111, v127
	v_exp_f32_e32 v112, v122
	v_exp_f32_e32 v113, v123
	v_exp_f32_e32 v122, v124
	v_exp_f32_e32 v123, v125
	s_waitcnt lgkmcnt(1)
	v_mfma_f32_32x32x16_bf16 v[80:95], v[102:105], v[98:101], v[80:95]
	v_exp_f32_e32 v124, v114
	s_waitcnt lgkmcnt(0)
	v_mfma_f32_32x32x16_bf16 v[64:79], v[106:109], v[98:101], v[64:79]
	v_add_f32_e32 v98, 0, v212
	v_add_f32_e32 v98, v216, v98
	v_add_f32_e32 v98, v213, v98
	v_add_f32_e32 v98, v217, v98
	v_add_f32_e32 v98, v214, v98
	v_add_f32_e32 v98, v218, v98
	v_add_f32_e32 v98, v215, v98
	v_add_f32_e32 v98, v219, v98
	v_add_f32_e32 v98, v183, v98
	v_add_f32_e32 v98, v187, v98
	v_add_f32_e32 v98, v184, v98
	v_add_f32_e32 v98, v188, v98
	v_exp_f32_e32 v108, v128
	v_add_f32_e32 v98, v185, v98
	v_exp_f32_e32 v109, v129
	v_add_f32_e32 v98, v189, v98
	v_add_f32_e32 v98, v186, v98
	v_add_f32_e32 v98, v211, v98
	v_add_f32_e32 v98, v108, v98
	v_add_f32_e32 v98, v109, v98
	v_add_f32_e32 v98, v110, v98
	v_add_f32_e32 v98, v111, v98
	v_add_f32_e32 v98, v112, v98
	v_add_f32_e32 v98, v113, v98
	v_add_f32_e32 v98, v118, v98
	v_add_f32_e32 v98, v119, v98
	v_add_f32_e32 v98, v116, v98
	v_add_f32_e32 v98, v117, v98
	v_add_f32_e32 v98, v122, v98
	v_add_f32_e32 v98, v123, v98
	v_add_f32_e32 v98, v120, v98
	v_add_f32_e32 v98, v121, v98
	v_add_f32_e32 v98, v124, v98
	v_add_f32_e32 v98, v115, v98
	v_mov_b32_e32 v99, v98
	v_cvt_pk_bf16_f32 v100, v212, v216
	v_cvt_pk_bf16_f32 v101, v213, v217
	v_cvt_pk_bf16_f32 v102, v214, v218
	v_cvt_pk_bf16_f32 v103, v215, v219
	s_nop 1
	v_permlane32_swap_b32_e32 v98, v99
	v_permlane32_swap_b32_e32 v100, v102
	v_permlane32_swap_b32_e32 v101, v103
	v_cvt_pk_bf16_f32 v104, v183, v187
	v_cvt_pk_bf16_f32 v105, v184, v188
	v_cvt_pk_bf16_f32 v106, v185, v189
	v_cvt_pk_bf16_f32 v107, v186, v211
	v_cvt_pk_bf16_f32 v108, v108, v109
	v_cvt_pk_bf16_f32 v109, v110, v111
	v_cvt_pk_bf16_f32 v110, v112, v113
	v_cvt_pk_bf16_f32 v111, v118, v119
	v_cvt_pk_bf16_f32 v112, v116, v117
	v_cvt_pk_bf16_f32 v113, v122, v123
	v_cvt_pk_bf16_f32 v114, v120, v121
	v_cvt_pk_bf16_f32 v115, v124, v115
	s_nop 0
	v_permlane32_swap_b32_e32 v104, v106
	v_permlane32_swap_b32_e32 v105, v107
	v_permlane32_swap_b32_e32 v108, v110
	v_permlane32_swap_b32_e32 v109, v111
	v_permlane32_swap_b32_e32 v112, v114
	v_permlane32_swap_b32_e32 v113, v115
	ds_read_b64_tr_b16 v[116:117], v160 offset:0
	ds_read_b64_tr_b16 v[118:119], v160 offset:0x800
	ds_read_b64_tr_b16 v[120:121], v160 offset:0x1000
	ds_read_b64_tr_b16 v[122:123], v160 offset:0x1800
	ds_read_b64_tr_b16 v[124:125], v160 offset:0x2000
	ds_read_b64_tr_b16 v[126:127], v160 offset:0x2800
	ds_read_b64_tr_b16 v[170:171], v160 offset:0x3000
	ds_read_b64_tr_b16 v[172:173], v160 offset:0x3800
	s_waitcnt lgkmcnt(0)
; #define SBAR() __builtin_amdgcn_sched_barrier(0)
; #define RESC(a) do { if (__any((a) < 1.f)) { if (hi == 0) al_l[r32] = (a); asm volatile("s_waitcnt lgkmcnt(0)" ::: "memory"); \
;     _Pragma("unroll") for (int d = 0; d < 4; ++d) _Pragma("unroll") for (int r = 0; r < 16; ++r) o[d][r] *= al_l[crow(r, hi)]; } } while (0)
; template <int D0> __device__ __forceinline__ void pv_one(f32x16& od, int vb, bf16x8 pa0, bf16x8 pa1, bf16x8 pa2, bf16x8 pa3) {
;     const s16x4 l0 = tr_read<v_rd_off(D0, 0, 0)>(vb), h0 = tr_read<v_rd_off(D0, 0, 1)>(vb), l1 = tr_read<v_rd_off(D0, 1, 0)>(vb), h1 = tr_read<v_rd_off(D0, 1, 1)>(vb);
;     const s16x4 l2 = tr_read<v_rd_off(D0, 2, 0)>(vb), h2 = tr_read<v_rd_off(D0, 2, 1)>(vb), l3 = tr_read<v_rd_off(D0, 3, 0)>(vb), h3 = tr_read<v_rd_off(D0, 3, 1)>(vb);
;     asm volatile("s_waitcnt lgkmcnt(0)" ::: "memory"); SBAR();
;     ...
;     od = __builtin_amdgcn_mfma_f32_32x32x16_bf16(pa0, PK(l0, h0), od, 0, 0, 0);
;     od = __builtin_amdgcn_mfma_f32_32x32x16_bf16(pa1, PK(l1, h1), od, 0, 0, 0);
;     od = __builtin_amdgcn_mfma_f32_32x32x16_bf16(pa2, PK(l2, h2), od, 0, 0, 0);
;     od = __builtin_amdgcn_mfma_f32_32x32x16_bf16(pa3, PK(l3, h3), od, 0, 0, 0);
;     ...
; }
; __device__ __forceinline__ void pv_d0(f32x16* o, int vb, bf16x8 pa0, bf16x8 pa1, bf16x8 pa2, bf16x8 pa3) {
;     pv_one<0>(o[0], vb, pa0, pa1, pa2, pa3); pv_one<1>(o[1], vb, pa0, pa1, pa2, pa3); pv_one<2>(o[2], vb, pa0, pa1, pa2, pa3); pv_one<3>(o[3], vb, pa0, pa1, pa2, pa3);
; }
; __device__ __forceinline__ void attn_unit(const bf16_t* Qb, const bf16_t* Kh, const bf16_t* Vh, bf16_t* Ob, float* scr, int seq, float lam, float onemli, const float* subg, char* lds) {
;     ...
;         pv_d0(o, vb0, pa0, pa1, pa2, pa3); partialSM(pB0, pB1, m_reg, mnB, alB);
;         __syncthreads(); RESC(alB);
	s_nop 0
	v_mfma_f32_32x32x16_bf16 v[48:63], v[100:103], v[116:119], v[48:63]
	ds_read_b64_tr_b16 v[116:117], v160 offset:0x200
	ds_read_b64_tr_b16 v[118:119], v160 offset:0xa00
	v_mfma_f32_32x32x16_bf16 v[48:63], v[104:107], v[120:123], v[48:63]
	ds_read_b64_tr_b16 v[120:121], v160 offset:0x1200
	ds_read_b64_tr_b16 v[122:123], v160 offset:0x1a00
	v_mfma_f32_32x32x16_bf16 v[48:63], v[108:111], v[124:127], v[48:63]
	ds_read_b64_tr_b16 v[124:125], v160 offset:0x2200
	ds_read_b64_tr_b16 v[126:127], v160 offset:0x2a00
	v_mfma_f32_32x32x16_bf16 v[48:63], v[112:115], v[170:173], v[48:63]
	ds_read_b64_tr_b16 v[170:171], v160 offset:0x3200
	ds_read_b64_tr_b16 v[172:173], v160 offset:0x3a00
	s_waitcnt lgkmcnt(0)
	v_mfma_f32_32x32x16_bf16 v[32:47], v[100:103], v[116:119], v[32:47]
	ds_read_b64_tr_b16 v[116:117], v160 offset:0x400
	ds_read_b64_tr_b16 v[118:119], v160 offset:0xc00
	v_mfma_f32_32x32x16_bf16 v[32:47], v[104:107], v[120:123], v[32:47]
	ds_read_b64_tr_b16 v[120:121], v160 offset:0x1400
	ds_read_b64_tr_b16 v[122:123], v160 offset:0x1c00
	v_mfma_f32_32x32x16_bf16 v[32:47], v[108:111], v[124:127], v[32:47]
	ds_read_b64_tr_b16 v[124:125], v160 offset:0x2400
	ds_read_b64_tr_b16 v[126:127], v160 offset:0x2c00
	v_mfma_f32_32x32x16_bf16 v[32:47], v[112:115], v[170:173], v[32:47]
	ds_read_b64_tr_b16 v[170:171], v160 offset:0x3400
	ds_read_b64_tr_b16 v[172:173], v160 offset:0x3c00
	s_waitcnt lgkmcnt(0)
	v_mfma_f32_32x32x16_bf16 v[16:31], v[100:103], v[116:119], v[16:31]
	ds_read_b64_tr_b16 v[116:117], v160 offset:0x600
	ds_read_b64_tr_b16 v[118:119], v160 offset:0xe00
	v_mfma_f32_32x32x16_bf16 v[16:31], v[104:107], v[120:123], v[16:31]
	ds_read_b64_tr_b16 v[120:121], v160 offset:0x1600
	ds_read_b64_tr_b16 v[122:123], v160 offset:0x1e00
	v_mfma_f32_32x32x16_bf16 v[16:31], v[108:111], v[124:127], v[16:31]
	ds_read_b64_tr_b16 v[124:125], v160 offset:0x2600
	ds_read_b64_tr_b16 v[126:127], v160 offset:0x2e00
	v_mfma_f32_32x32x16_bf16 v[16:31], v[112:115], v[170:173], v[16:31]
	ds_read_b64_tr_b16 v[170:171], v160 offset:0x3600
	ds_read_b64_tr_b16 v[172:173], v160 offset:0x3e00
	s_waitcnt lgkmcnt(0)
	v_mfma_f32_32x32x16_bf16 v[0:15], v[100:103], v[116:119], v[0:15]
	v_max_f32_e32 v100, v81, v81
	v_max_f32_e32 v101, v80, v80
	v_max_f32_e32 v100, v101, v100
	v_max3_f32 v100, v100, v82, v83
	v_max3_f32 v100, v100, v84, v85
	v_max3_f32 v100, v100, v86, v87
	v_max3_f32 v100, v100, v88, v89
	v_max3_f32 v100, v100, v90, v91
	v_max3_f32 v100, v100, v92, v93
	v_mfma_f32_32x32x16_bf16 v[0:15], v[104:107], v[120:123], v[0:15]
	v_max3_f32 v100, v100, v94, v95
	v_max3_f32 v100, v100, v64, v65
	v_max3_f32 v100, v100, v66, v67
	v_max3_f32 v100, v100, v68, v69
	v_max3_f32 v100, v100, v70, v71
	v_max3_f32 v100, v100, v72, v73
	v_max3_f32 v100, v100, v74, v75
	v_max3_f32 v100, v100, v76, v77
	v_mfma_f32_32x32x16_bf16 v[0:15], v[108:111], v[124:127], v[0:15]
	v_max3_f32 v100, v100, v78, v79
	v_mov_b32_e32 v101, v100
	s_nop 1
	v_permlane32_swap_b32_e32 v100, v101
	v_max_f32_e32 v101, v101, v101
	v_max_f32_e32 v100, v100, v100
	v_max_f32_e32 v100, v100, v101
	v_sub_f32_e32 v101, v100, v175
	v_cmp_ge_f32_e32 vcc, s65, v101
	v_max_f32_e32 v101, v175, v175
	v_max_f32_e32 v101, v101, v100
	v_mfma_f32_32x32x16_bf16 v[0:15], v[112:115], v[170:173], v[0:15]
	v_sub_f32_e32 v100, v175, v101
	v_mul_f32_e32 v100, 0x3e38aa3b, v100
	v_exp_f32_e32 v100, v100
	s_cmp_eq_u64 vcc, exec
	s_cselect_b64 s[8:9], -1, 0
	v_cndmask_b32_e64 v100, v100, 1.0, s[8:9]
	v_cmp_gt_f32_e32 vcc, 1.0, v100
	s_barrier
	s_cbranch_vccz .LBB0_276
	s_and_saveexec_b64 s[2:3], s[6:7]
	s_mov_b64 s[76:77], 0x800
	ds_write_b32 v157, v100 offset:128
	s_or_b64 exec, exec, s[2:3]
	s_waitcnt lgkmcnt(0)
	ds_read_b128 v[102:105], v158 offset:224
	ds_read_b128 v[106:109], v158 offset:192
	ds_read_b128 v[110:113], v158 offset:160
	ds_read_b128 v[114:117], v158 offset:128
	s_waitcnt lgkmcnt(3)
	v_pk_mul_f32 v[62:63], v[62:63], v[104:105]
	s_waitcnt lgkmcnt(2)
	v_pk_mul_f32 v[58:59], v[58:59], v[108:109]
	s_waitcnt lgkmcnt(1)
	v_pk_mul_f32 v[54:55], v[54:55], v[112:113]
	s_waitcnt lgkmcnt(0)
	v_pk_mul_f32 v[50:51], v[50:51], v[116:117]
	v_pk_mul_f32 v[60:61], v[60:61], v[102:103]
	v_pk_mul_f32 v[56:57], v[56:57], v[106:107]
	v_pk_mul_f32 v[52:53], v[52:53], v[110:111]
	v_pk_mul_f32 v[48:49], v[48:49], v[114:115]
	v_pk_mul_f32 v[46:47], v[46:47], v[104:105]
	v_pk_mul_f32 v[42:43], v[42:43], v[108:109]
	v_pk_mul_f32 v[38:39], v[38:39], v[112:113]
	v_pk_mul_f32 v[34:35], v[34:35], v[116:117]
	v_pk_mul_f32 v[44:45], v[44:45], v[102:103]
	v_pk_mul_f32 v[40:41], v[40:41], v[106:107]
	v_pk_mul_f32 v[36:37], v[36:37], v[110:111]
	v_pk_mul_f32 v[32:33], v[32:33], v[114:115]
	v_pk_mul_f32 v[30:31], v[30:31], v[104:105]
	v_pk_mul_f32 v[26:27], v[26:27], v[108:109]
	v_pk_mul_f32 v[22:23], v[22:23], v[112:113]
	v_pk_mul_f32 v[18:19], v[18:19], v[116:117]
	v_pk_mul_f32 v[28:29], v[28:29], v[102:103]
	v_pk_mul_f32 v[24:25], v[24:25], v[106:107]
	v_pk_mul_f32 v[20:21], v[20:21], v[110:111]
	v_pk_mul_f32 v[16:17], v[16:17], v[114:115]
	v_pk_mul_f32 v[14:15], v[14:15], v[104:105]
	v_pk_mul_f32 v[10:11], v[10:11], v[108:109]
	v_pk_mul_f32 v[6:7], v[6:7], v[112:113]
	v_pk_mul_f32 v[2:3], v[2:3], v[116:117]
	v_pk_mul_f32 v[12:13], v[12:13], v[102:103]
	v_pk_mul_f32 v[8:9], v[8:9], v[106:107]
	v_pk_mul_f32 v[4:5], v[4:5], v[110:111]
	v_pk_mul_f32 v[0:1], v[0:1], v[114:115]
	s_branch .LBB0_277

; #define SBAR() __builtin_amdgcn_sched_barrier(0)
; __device__ __forceinline__ void partialSM(f32x16& p0, f32x16& p1, float& m_reg, float& mn, float& alpha) {
;     ...
; #pragma unroll
;     for (int r = 0; r < 16; ++r) p0[r] = fmaf(p0[r], C, mnC);
; #pragma unroll
;     for (int r = 0; r < 16; ++r) p1[r] = fmaf(p1[r], C, mnC);
; #pragma unroll
;     for (int r = 0; r < 16; ++r) p0[r] = __builtin_amdgcn_exp2f(p0[r]);
; }
; __device__ __forceinline__ void finishSM(f32x16& p0, f32x16& p1, float alpha, float& l_reg, bf16x8& pa0, bf16x8& pa1, bf16x8& pa2, bf16x8& pa3) {
; #pragma unroll
;     for (int r = 0; r < 16; ++r) p1[r] = __builtin_amdgcn_exp2f(p1[r]);
;     float ps = 0;
; #pragma unroll
;     for (int r = 0; r < 16; ++r) ps += p0[r];
; #pragma unroll
;     for (int r = 0; r < 16; ++r) ps += p1[r];
;     { auto rr = __builtin_amdgcn_permlane32_swap(__float_as_uint(ps), __float_as_uint(ps), false, false);
;       ps = __uint_as_float(rr[0]) + __uint_as_float(rr[1]); }
;     l_reg = l_reg * alpha + ps;
;     ...
;     PK4(p0, 0, pa0); PK4(p0, 8, pa1); PK4(p1, 0, pa2); PK4(p1, 8, pa3);
;     ...
; }
; __device__ __forceinline__ void attn_unit(const bf16_t* Qb, const bf16_t* Kh, const bf16_t* Vh, bf16_t* Ob, float* scr, int seq, float lam, float onemli, const float* subg, char* lds) {
;     ...
;         finishSM(pB0, pB1, alB, l_reg, pa0, pa1, pa2, pa3); SBAR();
;         pv_d0(o, vb0 + (int)SHM_V, pa0, pa1, pa2, pa3);
.LBB0_277:
	v_cndmask_b32_e64 v101, v101, v175, s[8:9]
	v_mul_f32_e32 v101, 0xbe38aa3b, v101
	v_fmamk_f32 v80, v80, 0x3e38aa3b, v101
	v_fmamk_f32 v81, v81, 0x3e38aa3b, v101
	v_fmamk_f32 v102, v82, 0x3e38aa3b, v101
	v_exp_f32_e32 v82, v80
	v_fmamk_f32 v103, v84, 0x3e38aa3b, v101
	v_exp_f32_e32 v84, v81
	v_fmamk_f32 v83, v83, 0x3e38aa3b, v101
	v_exp_f32_e32 v80, v102
	v_fmamk_f32 v64, v64, 0x3e38aa3b, v101
	v_exp_f32_e32 v83, v83
	v_fmamk_f32 v104, v85, 0x3e38aa3b, v101
	v_fmamk_f32 v113, v94, 0x3e38aa3b, v101
	v_fmamk_f32 v94, v75, 0x3e38aa3b, v101
	v_exp_f32_e32 v75, v103
	v_exp_f32_e32 v102, v64
	v_add_f32_e32 v64, 0, v82
	v_fmamk_f32 v105, v86, 0x3e38aa3b, v101
	v_exp_f32_e32 v81, v104
	v_add_f32_e32 v64, v84, v64
	v_fmamk_f32 v106, v87, 0x3e38aa3b, v101
	v_fmamk_f32 v112, v93, 0x3e38aa3b, v101
	v_fmamk_f32 v93, v74, 0x3e38aa3b, v101
	v_exp_f32_e32 v74, v105
	v_add_f32_e32 v64, v80, v64
	v_fmamk_f32 v107, v88, 0x3e38aa3b, v101
	v_fmamk_f32 v114, v95, 0x3e38aa3b, v101
	v_fmamk_f32 v95, v76, 0x3e38aa3b, v101
	v_exp_f32_e32 v76, v106
	v_add_f32_e32 v64, v83, v64
	v_fmamk_f32 v108, v89, 0x3e38aa3b, v101
	v_fmamk_f32 v109, v90, 0x3e38aa3b, v101
	v_fmamk_f32 v90, v71, 0x3e38aa3b, v101
	v_exp_f32_e32 v71, v107
	v_add_f32_e32 v64, v75, v64
	v_fmamk_f32 v111, v92, 0x3e38aa3b, v101
	v_fmamk_f32 v92, v73, 0x3e38aa3b, v101
	v_exp_f32_e32 v73, v108
	v_add_f32_e32 v64, v81, v64
	v_fmamk_f32 v110, v91, 0x3e38aa3b, v101
	v_fmamk_f32 v88, v69, 0x3e38aa3b, v101
	v_exp_f32_e32 v69, v109
	v_add_f32_e32 v64, v74, v64
	v_fmamk_f32 v91, v72, 0x3e38aa3b, v101
	v_exp_f32_e32 v72, v110
	v_add_f32_e32 v64, v76, v64
	v_fmamk_f32 v86, v67, 0x3e38aa3b, v101
	v_exp_f32_e32 v67, v111
	v_add_f32_e32 v64, v71, v64
	v_fmamk_f32 v89, v70, 0x3e38aa3b, v101
	v_exp_f32_e32 v70, v112
	v_add_f32_e32 v64, v73, v64
	v_fmamk_f32 v85, v66, 0x3e38aa3b, v101
	v_exp_f32_e32 v66, v113
	v_add_f32_e32 v64, v69, v64
	v_fmamk_f32 v87, v68, 0x3e38aa3b, v101
	v_exp_f32_e32 v68, v114
	v_add_f32_e32 v64, v72, v64
	v_fmamk_f32 v65, v65, 0x3e38aa3b, v101
	v_add_f32_e32 v64, v67, v64
	v_exp_f32_e32 v103, v65
	v_add_f32_e32 v64, v70, v64
	v_exp_f32_e32 v85, v85
	v_add_f32_e32 v64, v66, v64
	v_exp_f32_e32 v86, v86
	v_add_f32_e32 v64, v68, v64
	v_exp_f32_e32 v87, v87
	v_add_f32_e32 v64, v102, v64
	v_exp_f32_e32 v88, v88
	v_add_f32_e32 v64, v103, v64
	v_exp_f32_e32 v89, v89
	v_add_f32_e32 v64, v85, v64
	v_exp_f32_e32 v90, v90
	v_add_f32_e32 v64, v86, v64
	v_exp_f32_e32 v91, v91
	v_add_f32_e32 v64, v87, v64
	v_exp_f32_e32 v92, v92
	v_add_f32_e32 v64, v88, v64
	v_exp_f32_e32 v93, v93
	v_add_f32_e32 v64, v89, v64
	v_exp_f32_e32 v94, v94
	v_add_f32_e32 v64, v90, v64
	v_fmamk_f32 v77, v77, 0x3e38aa3b, v101
	v_exp_f32_e32 v95, v95
	v_add_f32_e32 v64, v91, v64
	v_fmamk_f32 v78, v78, 0x3e38aa3b, v101
	v_exp_f32_e32 v104, v77
	v_add_f32_e32 v64, v92, v64
	v_fmac_f32_e32 v101, 0x3e38aa3b, v79
	v_exp_f32_e32 v105, v78
	v_add_f32_e32 v64, v93, v64
	v_exp_f32_e32 v101, v101
	v_add_f32_e32 v64, v94, v64
	v_add_f32_e32 v64, v95, v64
	v_add_f32_e32 v64, v104, v64
	v_add_f32_e32 v64, v105, v64
	v_add_f32_e32 v64, v101, v64
	v_mov_b32_e32 v65, v64
	s_nop 1
	v_permlane32_swap_b32_e32 v64, v65
	v_cvt_pk_bf16_f32 v78, v82, v84
	v_cvt_pk_bf16_f32 v79, v80, v83
	v_cvt_pk_bf16_f32 v80, v75, v81
	v_cvt_pk_bf16_f32 v81, v74, v76
	v_cvt_pk_bf16_f32 v74, v71, v73
	v_cvt_pk_bf16_f32 v75, v69, v72
	v_cvt_pk_bf16_f32 v76, v67, v70
	v_cvt_pk_bf16_f32 v77, v66, v68
	v_cvt_pk_bf16_f32 v66, v102, v103
	v_cvt_pk_bf16_f32 v67, v85, v86
	v_cvt_pk_bf16_f32 v68, v87, v88
	v_cvt_pk_bf16_f32 v69, v89, v90
	v_cvt_pk_bf16_f32 v70, v91, v92
	v_cvt_pk_bf16_f32 v71, v93, v94
	v_cvt_pk_bf16_f32 v72, v95, v104
	v_cvt_pk_bf16_f32 v73, v105, v101
	s_nop 0
	v_permlane32_swap_b32_e32 v78, v80
	v_permlane32_swap_b32_e32 v79, v81
	v_permlane32_swap_b32_e32 v74, v76
	v_permlane32_swap_b32_e32 v75, v77
	v_permlane32_swap_b32_e32 v66, v68
	v_permlane32_swap_b32_e32 v67, v69
	v_permlane32_swap_b32_e32 v70, v72
	v_permlane32_swap_b32_e32 v71, v73
	ds_read_b64_tr_b16 v[82:83], v159 offset:0
	ds_read_b64_tr_b16 v[84:85], v159 offset:0x800
	ds_read_b64_tr_b16 v[86:87], v159 offset:0x1000
	ds_read_b64_tr_b16 v[88:89], v159 offset:0x1800
	ds_read_b64_tr_b16 v[90:91], v159 offset:0x2000
	ds_read_b64_tr_b16 v[92:93], v159 offset:0x2800
	ds_read_b64_tr_b16 v[102:103], v159 offset:0x3000
	ds_read_b64_tr_b16 v[104:105], v159 offset:0x3800
	s_waitcnt lgkmcnt(0)
	s_nop 0
	v_mfma_f32_32x32x16_bf16 v[48:63], v[78:81], v[82:85], v[48:63]
	ds_read_b64_tr_b16 v[82:83], v159 offset:0x200
	ds_read_b64_tr_b16 v[84:85], v159 offset:0xa00
	v_mfma_f32_32x32x16_bf16 v[48:63], v[74:77], v[86:89], v[48:63]
	ds_read_b64_tr_b16 v[86:87], v159 offset:0x1200
	ds_read_b64_tr_b16 v[88:89], v159 offset:0x1a00
	v_mfma_f32_32x32x16_bf16 v[48:63], v[66:69], v[90:93], v[48:63]
	ds_read_b64_tr_b16 v[90:91], v159 offset:0x2200
	ds_read_b64_tr_b16 v[92:93], v159 offset:0x2a00
	v_mfma_f32_32x32x16_bf16 v[48:63], v[70:73], v[102:105], v[48:63]
	ds_read_b64_tr_b16 v[102:103], v159 offset:0x3200
	ds_read_b64_tr_b16 v[104:105], v159 offset:0x3a00
	s_waitcnt lgkmcnt(0)
	v_mfma_f32_32x32x16_bf16 v[32:47], v[78:81], v[82:85], v[32:47]
	ds_read_b64_tr_b16 v[82:83], v159 offset:0x400
	ds_read_b64_tr_b16 v[84:85], v159 offset:0xc00
	v_mfma_f32_32x32x16_bf16 v[32:47], v[74:77], v[86:89], v[32:47]
	ds_read_b64_tr_b16 v[86:87], v159 offset:0x1400
	ds_read_b64_tr_b16 v[88:89], v159 offset:0x1c00
	v_mfma_f32_32x32x16_bf16 v[32:47], v[66:69], v[90:93], v[32:47]
	ds_read_b64_tr_b16 v[90:91], v159 offset:0x2400
	ds_read_b64_tr_b16 v[92:93], v159 offset:0x2c00
	v_mfma_f32_32x32x16_bf16 v[32:47], v[70:73], v[102:105], v[32:47]
	ds_read_b64_tr_b16 v[102:103], v159 offset:0x3400
	ds_read_b64_tr_b16 v[104:105], v159 offset:0x3c00
	s_waitcnt lgkmcnt(0)
; __device__ __forceinline__ int crow(int r, int hi) { return (r & 3) + 8 * (r >> 2) + 4 * hi; }
; #define SWRITE(b, i) do { *(bf16x8*)(V_lds + (b) * SHM_V + vst0) = sr_[i].vs0;          \
;     *(bf16x8*)(V_lds + (b) * SHM_V + vst1) = sr_[i].vs1; int kc = sc * 2;               \
;     *(bf16x8*)(K_lds + (b) * SHM_K + KSWZ(sr, kc)) = sr_[i].ks0;                       \
;     *(bf16x8*)(K_lds + (b) * SHM_K + KSWZ(32 + sr, kc)) = sr_[i].ks1; } while (0)
; #define SWAIT() asm volatile("s_waitcnt vmcnt(0)" ::: "memory")
; __device__ __forceinline__ void attn_unit(const bf16_t* Qb, const bf16_t* Kh, const bf16_t* Vh, bf16_t* Ob, float* scr, int seq, float lam, float onemli, const float* subg, char* lds) {
;     ...
;         float m_reg = -1e30f, l_reg = 0; f32x16 o[4] = {}; bf16x8 qr[4];
;         const unsigned qoff = (unsigned)((wid * 32 + r32) * LD + comp * 64 + hi * 8) * 2u;
; #pragma unroll
;         for (int d0 = 0; d0 < 4; ++d0) qr[d0] = *reinterpret_cast<const bf16x8*>((const char*)Qb + qoff + d0 * 32);
;         struct { bf16x8 vs0, vs1, ks0, ks1; } sr_[1];
;     ...
;         f32x16 pA0, pA1, pB0, pB1; float mnA, mnB, alA, alB; bf16x8 pa0, pa1, pa2, pa3;
;         constexpr int SE = 0, SO = 0;
;         __syncthreads();
;         SLOAD(SE, 0); asm volatile("s_waitcnt vmcnt(0)" ::: "memory"); SWRITE(0, SE); __syncthreads();
;         qkt(pA0, pA1, K_lds, qr, r32, hi, comp); partialSM(pA0, pA1, m_reg, mnA, alA);
;         SLOAD(SO, KVBLK);
;         SWAIT(); SWRITE(1, SO); __syncthreads();
;     ...
;         pv_d0(o, vb0 + (int)SHM_V, pa0, pa1, pa2, pa3);
;         if (hi == 0) li_l[r32] = l_reg; asm volatile("s_waitcnt lgkmcnt(0)" ::: "memory");
;         float rli[16];
; #pragma unroll
;         for (int r = 0; r < 16; ++r) rli[r] = __builtin_amdgcn_rcpf(li_l[crow(r, hi)]);
;         unsigned soff = (unsigned)((wid * 64 + lane) * 256); asm volatile("" : "+v"(soff));
;         f32x4* sw = (f32x4*)((char*)scr + soff);
;         if (comp == 0) {
; #pragma unroll
;             for (int d0 = 0; d0 < 4; ++d0)
; #pragma unroll
;                 for (int r = 0; r < 16; r += 4) sw[d0 * 4 + (r >> 2)] = (f32x4){o[d0][r] * rli[r], o[d0][r + 1] * rli[r + 1], o[d0][r + 2] * rli[r + 2], o[d0][r + 3] * rli[r + 3]};
	v_mfma_f32_32x32x16_bf16 v[16:31], v[78:81], v[82:85], v[16:31]
	ds_read_b64_tr_b16 v[82:83], v159 offset:0x600
	ds_read_b64_tr_b16 v[84:85], v159 offset:0xe00
	v_mfma_f32_32x32x16_bf16 v[16:31], v[74:77], v[86:89], v[16:31]
	ds_read_b64_tr_b16 v[86:87], v159 offset:0x1600
	ds_read_b64_tr_b16 v[88:89], v159 offset:0x1e00
	v_mfma_f32_32x32x16_bf16 v[16:31], v[66:69], v[90:93], v[16:31]
	ds_read_b64_tr_b16 v[90:91], v159 offset:0x2600
	ds_read_b64_tr_b16 v[92:93], v159 offset:0x2e00
	v_mfma_f32_32x32x16_bf16 v[16:31], v[70:73], v[102:105], v[16:31]
	ds_read_b64_tr_b16 v[102:103], v159 offset:0x3600
	ds_read_b64_tr_b16 v[104:105], v159 offset:0x3e00
	s_waitcnt lgkmcnt(0)
	v_mfma_f32_32x32x16_bf16 v[0:15], v[78:81], v[82:85], v[0:15]
	v_mfma_f32_32x32x16_bf16 v[0:15], v[74:77], v[86:89], v[0:15]
	v_mfma_f32_32x32x16_bf16 v[0:15], v[66:69], v[90:93], v[0:15]
	v_mfma_f32_32x32x16_bf16 v[0:15], v[70:73], v[102:105], v[0:15]
	s_and_saveexec_b64 s[2:3], s[6:7]
	v_add_f32_e32 v66, v98, v99
	v_fmac_f32_e32 v66, v169, v179
	v_add_f32_e32 v64, v64, v65
	v_fmac_f32_e32 v64, v66, v100
	ds_write_b32 v157, v64
	s_or_b64 exec, exec, s[2:3]
	s_waitcnt lgkmcnt(0)
	ds_read_b128 v[64:67], v158
	ds_read_b128 v[68:71], v158 offset:32
	ds_read_b128 v[72:75], v158 offset:64
	ds_read_b128 v[76:79], v158 offset:96
	v_lshlrev_b32_e32 v165, 8, v165
	s_waitcnt lgkmcnt(3)
	v_rcp_f32_e32 v67, v67
	v_rcp_f32_e32 v66, v66
	v_rcp_f32_e32 v65, v65
	v_rcp_f32_e32 v64, v64
	s_waitcnt lgkmcnt(2)
	v_rcp_f32_e32 v71, v71
	v_rcp_f32_e32 v70, v70
	v_rcp_f32_e32 v69, v69
	v_rcp_f32_e32 v68, v68
	s_waitcnt lgkmcnt(1)
	v_rcp_f32_e32 v75, v75
	v_rcp_f32_e32 v74, v74
	v_rcp_f32_e32 v73, v73
	v_rcp_f32_e32 v72, v72
	s_waitcnt lgkmcnt(0)
	v_rcp_f32_e32 v79, v79
	v_rcp_f32_e32 v78, v78
	v_rcp_f32_e32 v77, v77
	v_rcp_f32_e32 v76, v76
	v_mov_b32_e32 v80, v165
	v_pk_mul_f32 v[48:49], v[48:49], v[64:65]
	v_pk_mul_f32 v[50:51], v[50:51], v[66:67]
	v_pk_mul_f32 v[32:33], v[32:33], v[64:65]
	v_pk_mul_f32 v[34:35], v[34:35], v[66:67]
	v_pk_mul_f32 v[16:17], v[16:17], v[64:65]
	v_pk_mul_f32 v[18:19], v[18:19], v[66:67]
	v_pk_mul_f32 v[0:1], v[0:1], v[64:65]
	v_pk_mul_f32 v[2:3], v[2:3], v[66:67]
	global_store_dwordx4 v80, v[48:51], s[12:13]
	global_store_dwordx4 v80, v[32:35], s[12:13] offset:64
	global_store_dwordx4 v80, v[16:19], s[12:13] offset:128
	v_pk_mul_f32 v[48:49], v[52:53], v[68:69]
	v_pk_mul_f32 v[50:51], v[54:55], v[70:71]
	v_pk_mul_f32 v[32:33], v[36:37], v[68:69]
	v_pk_mul_f32 v[34:35], v[38:39], v[70:71]
	v_pk_mul_f32 v[16:17], v[20:21], v[68:69]
	v_pk_mul_f32 v[18:19], v[22:23], v[70:71]
	global_store_dwordx4 v80, v[0:3], s[12:13] offset:192
	global_store_dwordx4 v80, v[48:51], s[12:13] offset:16
	global_store_dwordx4 v80, v[32:35], s[12:13] offset:80
	v_pk_mul_f32 v[0:1], v[4:5], v[68:69]
	v_pk_mul_f32 v[2:3], v[6:7], v[70:71]
	v_pk_mul_f32 v[48:49], v[56:57], v[72:73]
	v_pk_mul_f32 v[50:51], v[58:59], v[74:75]
	v_pk_mul_f32 v[32:33], v[40:41], v[72:73]
	v_pk_mul_f32 v[34:35], v[42:43], v[74:75]
	global_store_dwordx4 v80, v[16:19], s[12:13] offset:144
	global_store_dwordx4 v80, v[0:3], s[12:13] offset:208
	global_store_dwordx4 v80, v[48:51], s[12:13] offset:32
	v_pk_mul_f32 v[16:17], v[24:25], v[72:73]
	v_pk_mul_f32 v[18:19], v[26:27], v[74:75]
	v_pk_mul_f32 v[0:1], v[8:9], v[72:73]
	v_pk_mul_f32 v[2:3], v[10:11], v[74:75]
	v_pk_mul_f32 v[48:49], v[60:61], v[76:77]
	v_pk_mul_f32 v[50:51], v[62:63], v[78:79]
	global_store_dwordx4 v80, v[32:35], s[12:13] offset:96
	global_store_dwordx4 v80, v[16:19], s[12:13] offset:160
	global_store_dwordx4 v80, v[0:3], s[12:13] offset:224
	v_pk_mul_f32 v[32:33], v[44:45], v[76:77]
	v_pk_mul_f32 v[34:35], v[46:47], v[78:79]
	v_pk_mul_f32 v[16:17], v[28:29], v[76:77]
	v_pk_mul_f32 v[18:19], v[30:31], v[78:79]
	v_pk_mul_f32 v[0:1], v[12:13], v[76:77]
	v_pk_mul_f32 v[2:3], v[14:15], v[78:79]
	global_store_dwordx4 v80, v[48:51], s[12:13] offset:48
	global_store_dwordx4 v80, v[32:35], s[12:13] offset:112
	global_store_dwordx4 v80, v[16:19], s[12:13] offset:176
	global_store_dwordx4 v80, v[0:3], s[12:13] offset:240
	global_load_dwordx4 v[110:113], v[148:149], off offset:128
	global_load_dwordx4 v[106:109], v[148:149], off offset:160
	global_load_dwordx4 v[102:105], v[148:149], off offset:192
	global_load_dwordx4 v[98:101], v[148:149], off offset:224
	s_barrier
	global_load_dwordx4 v[0:3], v[140:141], off
	global_load_dwordx4 v[4:7], v[142:143], off
	global_load_dwordx4 v[8:11], v[144:145], off
	global_load_dwordx4 v[12:15], v[146:147], off
	s_waitcnt vmcnt(0)
	v_or_b32_e32 v48, 0xa0, v166
	v_bitop3_b32 v48, v48, v167, v168 bitop3:0xde
	v_add_u32_e32 v143, 0, v48
	s_mov_b32 s36, s37
	s_mov_b32 s38, s37
	s_mov_b32 s39, s37
	s_mov_b32 s40, s37
	s_mov_b32 s41, s37
	s_mov_b32 s42, s37
	s_mov_b32 s43, s37
	s_mov_b32 s44, s37
	s_mov_b32 s45, s37
	s_mov_b32 s46, s37
	s_mov_b32 s47, s37
	s_mov_b32 s48, s37
	s_mov_b32 s49, s37
	s_mov_b32 s50, s37
	s_waitcnt vmcnt(3)
	ds_write_b128 v163, v[0:3]
	s_waitcnt vmcnt(2)
	ds_write_b128 v164, v[4:7]
	s_waitcnt vmcnt(1)
	ds_write_b128 v161, v[8:11] offset:32768
	s_waitcnt vmcnt(0)
	ds_write_b128 v162, v[12:15] offset:32768
	v_or_b32_e32 v0, 0x80, v166
	v_bitop3_b32 v0, v0, v167, v168 bitop3:0xde
	v_add_u32_e32 v140, 0, v0
	s_waitcnt lgkmcnt(0)
	s_barrier
; #define SWRITE(b, i) do { *(bf16x8*)(V_lds + (b) * SHM_V + vst0) = sr_[i].vs0;          \
;     *(bf16x8*)(V_lds + (b) * SHM_V + vst1) = sr_[i].vs1; int kc = sc * 2;               \
;     *(bf16x8*)(K_lds + (b) * SHM_K + KSWZ(sr, kc)) = sr_[i].ks0;                       \
;     *(bf16x8*)(K_lds + (b) * SHM_K + KSWZ(32 + sr, kc)) = sr_[i].ks1; } while (0)
; #define SWAIT() asm volatile("s_waitcnt vmcnt(0)" ::: "memory")
; __device__ __forceinline__ void partialSM(f32x16& p0, f32x16& p1, float& m_reg, float& mn, float& alpha) {
;     constexpr float C = SCALE * 1.4426950408889634f;
;     float pmax = p0[0];
; #pragma unroll
;     for (int r = 1; r < 16; ++r) pmax = fmaxf(pmax, p0[r]);
; #pragma unroll
;     for (int r = 0; r < 16; ++r) pmax = fmaxf(pmax, p1[r]);
;     { auto rr = __builtin_amdgcn_permlane32_swap(__float_as_uint(pmax), __float_as_uint(pmax), false, false);
;       pmax = fmaxf(__uint_as_float(rr[0]), __uint_as_float(rr[1])); }
;     if (__builtin_expect(__all(pmax - m_reg <= THR / SCALE), 1)) { mn = m_reg; alpha = 1.f; }
;     else { mn = fmaxf(m_reg, pmax); alpha = __builtin_amdgcn_exp2f((m_reg - mn) * C); m_reg = mn; }
;     const float mnC = -mn * C;
; #pragma unroll
;     for (int r = 0; r < 16; ++r) p0[r] = fmaf(p0[r], C, mnC);
; #pragma unroll
;     for (int r = 0; r < 16; ++r) p1[r] = fmaf(p1[r], C, mnC);
; #pragma unroll
;     for (int r = 0; r < 16; ++r) p0[r] = __builtin_amdgcn_exp2f(p0[r]);
; }
; __device__ __forceinline__ void attn_unit(const bf16_t* Qb, const bf16_t* Kh, const bf16_t* Vh, bf16_t* Ob, float* scr, int seq, float lam, float onemli, const float* subg, char* lds) {
;     ...
;         SLOAD(SE, 0); asm volatile("s_waitcnt vmcnt(0)" ::: "memory"); SWRITE(0, SE); __syncthreads();
;         qkt(pA0, pA1, K_lds, qr, r32, hi, comp); partialSM(pA0, pA1, m_reg, mnA, alA);
;         SLOAD(SO, KVBLK);
;         SWAIT(); SWRITE(1, SO); __syncthreads();
	ds_read_b128 v[16:19], v140 offset:32768
	ds_read_b128 v[32:35], v140 offset:40960
	s_waitcnt lgkmcnt(1)
	v_mfma_f32_32x32x16_bf16 v[16:31], v[16:19], v[110:113], 0
	ds_read_b128 v[48:51], v143 offset:32768
	ds_read_b128 v[52:55], v143 offset:40960
	s_mov_b32 s51, s37
	v_mov_b64_e32 v[0:1], s[36:37]
	v_mov_b64_e32 v[14:15], s[50:51]
	v_mov_b64_e32 v[2:3], s[38:39]
	v_mov_b64_e32 v[4:5], s[40:41]
	v_mov_b64_e32 v[6:7], s[42:43]
	s_waitcnt lgkmcnt(2)
	v_mfma_f32_32x32x16_bf16 v[32:47], v[32:35], v[110:113], 0
	v_mov_b64_e32 v[8:9], s[44:45]
	v_mov_b64_e32 v[10:11], s[46:47]
	v_mov_b64_e32 v[12:13], s[48:49]
	s_mov_b32 s36, 2
	s_waitcnt lgkmcnt(1)
	v_mfma_f32_32x32x16_bf16 v[16:31], v[48:51], v[106:109], v[16:31]
	v_or_b32_e32 v48, 0xc0, v166
	v_bitop3_b32 v48, v48, v167, v168 bitop3:0xde
	v_add_u32_e32 v142, 0, v48
	s_waitcnt lgkmcnt(0)
	v_mfma_f32_32x32x16_bf16 v[32:47], v[52:55], v[106:109], v[32:47]
	ds_read_b128 v[48:51], v142 offset:32768
	ds_read_b128 v[52:55], v142 offset:40960
	s_waitcnt lgkmcnt(1)
	v_mfma_f32_32x32x16_bf16 v[16:31], v[48:51], v[102:105], v[16:31]
	v_or_b32_e32 v48, 0xe0, v166
	v_bitop3_b32 v48, v48, v167, v168 bitop3:0xde
	v_add_u32_e32 v141, 0, v48
	s_waitcnt lgkmcnt(0)
	v_mfma_f32_32x32x16_bf16 v[32:47], v[52:55], v[102:105], v[32:47]
	ds_read_b128 v[48:51], v141 offset:32768
	ds_read_b128 v[52:55], v141 offset:40960
	s_waitcnt lgkmcnt(1)
	v_mfma_f32_32x32x16_bf16 v[16:31], v[48:51], v[98:101], v[16:31]
	s_waitcnt lgkmcnt(0)
	v_mfma_f32_32x32x16_bf16 v[32:47], v[52:55], v[98:101], v[32:47]
	s_nop 9
	v_max_f32_e32 v48, v17, v17
	v_max_f32_e32 v49, v16, v16
	v_max_f32_e32 v48, v49, v48
	v_max3_f32 v48, v48, v18, v19
	v_max3_f32 v48, v48, v20, v21
	v_max3_f32 v48, v48, v22, v23
	v_max3_f32 v48, v48, v24, v25
	v_max3_f32 v48, v48, v26, v27
	v_max3_f32 v48, v48, v28, v29
	v_max3_f32 v48, v48, v30, v31
	v_max3_f32 v48, v48, v32, v33
	v_max3_f32 v48, v48, v34, v35
	v_max3_f32 v48, v48, v36, v37
	v_max3_f32 v48, v48, v38, v39
	v_max3_f32 v48, v48, v40, v41
	v_max3_f32 v48, v48, v42, v43
	v_max3_f32 v48, v48, v44, v45
	v_max3_f32 v48, v48, v46, v47
	v_mov_b32_e32 v49, v48
	s_nop 1
	v_permlane32_swap_b32_e32 v48, v49
	v_max_f32_e32 v49, v49, v49
	v_max_f32_e32 v48, v48, v48
	v_max_f32_e32 v64, v48, v49
	v_add_f32_e32 v48, 0x7149f2ca, v64
	v_cmp_ge_f32_e32 vcc, s65, v48
	global_load_dwordx4 v[48:51], v[132:133], off
	global_load_dwordx4 v[52:55], v[138:139], off
	global_load_dwordx4 v[56:59], v[134:135], off
	global_load_dwordx4 v[60:63], v[136:137], off
	s_waitcnt vmcnt(0)
	s_waitcnt vmcnt(3)
	ds_write_b128 v163, v[48:51] offset:16384
	s_waitcnt vmcnt(2)
	ds_write_b128 v164, v[52:55] offset:16384
	s_waitcnt vmcnt(1)
	ds_write_b128 v161, v[56:59] offset:49152
	s_waitcnt vmcnt(0)
	ds_write_b128 v162, v[60:63] offset:49152
	v_max_f32_e32 v48, 0xf149f2ca, v64
	v_sub_f32_e32 v49, 0xf149f2ca, v48
	v_mul_f32_e32 v49, 0x3e38aa3b, v49
	v_exp_f32_e32 v49, v49
	s_cmp_eq_u64 vcc, exec
	s_cselect_b64 vcc, -1, 0
	v_mov_b32_e32 v132, 0
	v_cndmask_b32_e64 v133, v49, 1.0, vcc
	v_mov_b32_e32 v49, 0xf149f2ca
	v_cndmask_b32_e32 v134, v48, v49, vcc
	v_mul_f32_e32 v48, 0xbe38aa3b, v134
	v_fmamk_f32 v16, v16, 0x3e38aa3b, v48
	v_exp_f32_e32 v169, v16
	v_fmamk_f32 v16, v17, 0x3e38aa3b, v48
	v_exp_f32_e32 v173, v16
	v_fmamk_f32 v16, v18, 0x3e38aa3b, v48
	v_exp_f32_e32 v170, v16
	v_fmamk_f32 v16, v19, 0x3e38aa3b, v48
	v_exp_f32_e32 v174, v16
	v_fmamk_f32 v16, v20, 0x3e38aa3b, v48
	v_exp_f32_e32 v171, v16
	v_fmamk_f32 v16, v21, 0x3e38aa3b, v48
	v_exp_f32_e32 v175, v16
	v_fmamk_f32 v16, v22, 0x3e38aa3b, v48
	v_exp_f32_e32 v172, v16
	v_fmamk_f32 v16, v23, 0x3e38aa3b, v48
	v_exp_f32_e32 v176, v16
	v_fmamk_f32 v16, v24, 0x3e38aa3b, v48
	v_exp_f32_e32 v145, v16
	v_fmamk_f32 v16, v25, 0x3e38aa3b, v48
	v_exp_f32_e32 v149, v16
	v_fmamk_f32 v16, v26, 0x3e38aa3b, v48
	v_exp_f32_e32 v146, v16
	v_fmamk_f32 v16, v27, 0x3e38aa3b, v48
	v_exp_f32_e32 v166, v16
	v_fmamk_f32 v16, v28, 0x3e38aa3b, v48
	v_exp_f32_e32 v147, v16
	v_fmamk_f32 v16, v29, 0x3e38aa3b, v48
	v_pk_fma_f32 v[114:115], v[46:47], s[72:73], v[48:49] op_sel_hi:[1,0,0]
	v_pk_fma_f32 v[120:121], v[44:45], s[72:73], v[48:49] op_sel_hi:[1,0,0]
	v_pk_fma_f32 v[124:125], v[42:43], s[72:73], v[48:49] op_sel_hi:[1,0,0]
	v_pk_fma_f32 v[116:117], v[40:41], s[72:73], v[48:49] op_sel_hi:[1,0,0]
	v_pk_fma_f32 v[118:119], v[38:39], s[72:73], v[48:49] op_sel_hi:[1,0,0]
	v_pk_fma_f32 v[122:123], v[36:37], s[72:73], v[48:49] op_sel_hi:[1,0,0]
	v_pk_fma_f32 v[126:127], v[34:35], s[72:73], v[48:49] op_sel_hi:[1,0,0]
	v_pk_fma_f32 v[128:129], v[32:33], s[72:73], v[48:49] op_sel_hi:[1,0,0]
	v_exp_f32_e32 v167, v16
	v_fmamk_f32 v16, v30, 0x3e38aa3b, v48
	v_fmac_f32_e32 v48, 0x3e38aa3b, v31
	v_exp_f32_e32 v148, v16
	v_exp_f32_e32 v168, v48
	v_mov_b64_e32 v[30:31], v[14:15]
	v_mov_b64_e32 v[46:47], v[14:15]
	v_mov_b64_e32 v[62:63], v[14:15]
	v_mov_b64_e32 v[28:29], v[12:13]
	v_mov_b64_e32 v[26:27], v[10:11]
	v_mov_b64_e32 v[24:25], v[8:9]
	v_mov_b64_e32 v[22:23], v[6:7]
	v_mov_b64_e32 v[20:21], v[4:5]
	v_mov_b64_e32 v[18:19], v[2:3]
	v_mov_b64_e32 v[16:17], v[0:1]
	v_mov_b64_e32 v[44:45], v[12:13]
	v_mov_b64_e32 v[42:43], v[10:11]
	v_mov_b64_e32 v[40:41], v[8:9]
	v_mov_b64_e32 v[38:39], v[6:7]
	v_mov_b64_e32 v[36:37], v[4:5]
	v_mov_b64_e32 v[34:35], v[2:3]
	v_mov_b64_e32 v[32:33], v[0:1]
	v_mov_b64_e32 v[60:61], v[12:13]
	v_mov_b64_e32 v[58:59], v[10:11]
	v_mov_b64_e32 v[56:57], v[8:9]
	v_mov_b64_e32 v[54:55], v[6:7]
	v_mov_b64_e32 v[52:53], v[4:5]
	v_mov_b64_e32 v[50:51], v[2:3]
	v_mov_b64_e32 v[48:49], v[0:1]
	s_waitcnt lgkmcnt(0)
	s_barrier
	v_mov_b32_e32 v240, v169
	v_mov_b32_e32 v241, v173
	v_mov_b32_e32 v242, v170
	v_mov_b32_e32 v243, v174
	v_mov_b32_e32 v244, v171
	v_mov_b32_e32 v245, v175
	v_mov_b32_e32 v246, v172
	v_mov_b32_e32 v247, v176
	v_mov_b32_e32 v248, v145
	v_mov_b32_e32 v249, v149
	v_mov_b32_e32 v250, v146
	v_mov_b32_e32 v251, v166
	v_mov_b32_e32 v206, v147
	v_mov_b32_e32 v207, v167
	v_mov_b32_e32 v208, v148
	v_mov_b32_e32 v209, v168
; #define SBAR() __builtin_amdgcn_sched_barrier(0)
; __device__ __forceinline__ void finishSM(f32x16& p0, f32x16& p1, float alpha, float& l_reg, bf16x8& pa0, bf16x8& pa1, bf16x8& pa2, bf16x8& pa3) {
; #pragma unroll
;     for (int r = 0; r < 16; ++r) p1[r] = __builtin_amdgcn_exp2f(p1[r]);
;     float ps = 0;
; #pragma unroll
;     for (int r = 0; r < 16; ++r) ps += p0[r];
; #pragma unroll
;     for (int r = 0; r < 16; ++r) ps += p1[r];
;     { auto rr = __builtin_amdgcn_permlane32_swap(__float_as_uint(ps), __float_as_uint(ps), false, false);
;       ps = __uint_as_float(rr[0]) + __uint_as_float(rr[1]); }
;     l_reg = l_reg * alpha + ps;
;     ...
;     PK4(p0, 0, pa0); PK4(p0, 8, pa1); PK4(p1, 0, pa2); PK4(p1, 8, pa3);
;     ...
; }
; __device__ __forceinline__ void attn_unit(const bf16_t* Qb, const bf16_t* Kh, const bf16_t* Vh, bf16_t* Ob, float* scr, int seq, float lam, float onemli, const float* subg, char* lds) {
;     ...
;         for (int j = 1; j + 1 < NT; j += 2) {
;             SBAR(); qkt(pB0, pB1, K_lds + SHM_K, qr, r32, hi, comp);
;             finishSM(pA0, pA1, alA, l_reg, pa0, pa1, pa2, pa3); SBAR();
;             SLOAD(SO, (j + 1) * KVBLK); SBAR();
;             pv_d0(o, vb0, pa0, pa1, pa2, pa3); partialSM(pB0, pB1, m_reg, mnB, alB);
.LBB0_280:
	ds_read_b128 v[64:67], v140 offset:49152
	ds_read_b128 v[68:71], v140 offset:57344
	v_add_f32_e32 v135, 0, v240
	v_add_f32_e32 v135, v241, v135
	v_add_f32_e32 v135, v242, v135
	s_waitcnt lgkmcnt(1)
	v_mfma_f32_32x32x16_bf16 v[80:95], v[64:67], v[110:113], 0
	v_add_f32_e32 v135, v243, v135
	v_add_f32_e32 v135, v244, v135
	ds_read_b128 v[136:139], v143 offset:49152
	ds_read_b128 v[178:181], v143 offset:57344
	v_add_f32_e32 v135, v245, v135
	v_add_f32_e32 v135, v246, v135
	v_add_f32_e32 v135, v247, v135
	v_add_f32_e32 v135, v248, v135
	s_waitcnt lgkmcnt(2)
	v_mfma_f32_32x32x16_bf16 v[64:79], v[68:71], v[110:113], 0
	v_add_f32_e32 v135, v249, v135
	v_add_f32_e32 v135, v250, v135
	v_add_f32_e32 v135, v251, v135
	v_exp_f32_e32 v128, v128
	v_add_f32_e32 v135, v206, v135
	v_exp_f32_e32 v129, v129
	v_add_f32_e32 v135, v207, v135
	s_waitcnt lgkmcnt(1)
	v_mfma_f32_32x32x16_bf16 v[80:95], v[136:139], v[106:109], v[80:95]
	v_exp_f32_e32 v126, v126
	v_add_f32_e32 v135, v208, v135
	v_exp_f32_e32 v127, v127
	v_add_f32_e32 v135, v209, v135
	v_exp_f32_e32 v122, v122
	v_add_f32_e32 v135, v128, v135
	v_exp_f32_e32 v123, v123
	s_waitcnt lgkmcnt(0)
	v_mfma_f32_32x32x16_bf16 v[64:79], v[178:181], v[106:109], v[64:79]
	ds_read_b128 v[136:139], v142 offset:49152
	ds_read_b128 v[178:181], v142 offset:57344
	v_add_f32_e32 v135, v129, v135
	v_exp_f32_e32 v118, v118
	v_add_f32_e32 v135, v126, v135
	v_exp_f32_e32 v119, v119
	v_add_f32_e32 v135, v127, v135
	v_exp_f32_e32 v116, v116
	s_waitcnt lgkmcnt(1)
	v_mfma_f32_32x32x16_bf16 v[80:95], v[136:139], v[102:105], v[80:95]
	v_add_f32_e32 v135, v122, v135
	v_exp_f32_e32 v117, v117
	v_add_f32_e32 v135, v123, v135
	v_exp_f32_e32 v124, v124
	v_add_f32_e32 v135, v118, v135
	v_exp_f32_e32 v125, v125
	v_add_f32_e32 v135, v119, v135
	s_waitcnt lgkmcnt(0)
	v_mfma_f32_32x32x16_bf16 v[64:79], v[178:181], v[102:105], v[64:79]
	ds_read_b128 v[136:139], v141 offset:49152
	ds_read_b128 v[178:181], v141 offset:57344
	v_exp_f32_e32 v120, v120
	v_add_f32_e32 v135, v116, v135
	v_exp_f32_e32 v121, v121
	v_add_f32_e32 v135, v117, v135
	v_exp_f32_e32 v114, v114
	v_add_f32_e32 v135, v124, v135
	s_waitcnt lgkmcnt(1)
	v_mfma_f32_32x32x16_bf16 v[80:95], v[136:139], v[98:101], v[80:95]
	v_exp_f32_e32 v115, v115
	v_add_f32_e32 v135, v125, v135
	v_add_f32_e32 v135, v120, v135
	v_add_f32_e32 v135, v121, v135
	v_add_f32_e32 v135, v114, v135
	v_add_f32_e32 v135, v115, v135
	v_mov_b32_e32 v136, v135
	s_waitcnt lgkmcnt(0)
	v_mfma_f32_32x32x16_bf16 v[64:79], v[178:181], v[98:101], v[64:79]
	v_permlane32_swap_b32_e32 v135, v136
	v_cvt_pk_bf16_f32 v178, v240, v241
	v_cvt_pk_bf16_f32 v179, v242, v243
	v_cvt_pk_bf16_f32 v180, v244, v245
	v_cvt_pk_bf16_f32 v181, v246, v247
	v_cvt_pk_bf16_f32 v144, v248, v249
	v_cvt_pk_bf16_f32 v145, v250, v251
	v_cvt_pk_bf16_f32 v146, v206, v207
	v_cvt_pk_bf16_f32 v147, v208, v209
	v_cvt_pk_bf16_f32 v166, v128, v129
	v_cvt_pk_bf16_f32 v167, v126, v127
	v_cvt_pk_bf16_f32 v168, v122, v123
	v_cvt_pk_bf16_f32 v169, v118, v119
	v_cvt_pk_bf16_f32 v170, v116, v117
	v_cvt_pk_bf16_f32 v171, v124, v125
	v_cvt_pk_bf16_f32 v172, v120, v121
	v_cvt_pk_bf16_f32 v173, v114, v115
	s_nop 0
	v_permlane32_swap_b32_e32 v178, v180
	v_permlane32_swap_b32_e32 v179, v181
	v_permlane32_swap_b32_e32 v144, v146
	v_permlane32_swap_b32_e32 v145, v147
	v_permlane32_swap_b32_e32 v166, v168
	v_permlane32_swap_b32_e32 v167, v169
	v_permlane32_swap_b32_e32 v170, v172
	v_permlane32_swap_b32_e32 v171, v173
	v_add_u32_e32 v122, 0x10000, v96
	global_load_dwordx4 v[240:243], v96, s[58:59]
	global_load_dwordx4 v[244:247], v96, s[28:29]
	global_load_dwordx4 v[206:209], v122, s[58:59]
	s_nop 0
	global_load_dwordx4 v[248:251], v122, s[28:29]
	ds_read_b64_tr_b16 v[174:175], v160 offset:0
	ds_read_b64_tr_b16 v[176:177], v160 offset:0x800
	ds_read_b64_tr_b16 v[182:183], v160 offset:0x1000
	ds_read_b64_tr_b16 v[184:185], v160 offset:0x1800
	ds_read_b64_tr_b16 v[186:187], v160 offset:0x2000
	ds_read_b64_tr_b16 v[188:189], v160 offset:0x2800
	ds_read_b64_tr_b16 v[212:213], v160 offset:0x3000
	ds_read_b64_tr_b16 v[214:215], v160 offset:0x3800
	s_waitcnt lgkmcnt(0)
	s_nop 0
	v_mfma_f32_32x32x16_bf16 v[48:63], v[178:181], v[174:177], v[48:63]
	ds_read_b64_tr_b16 v[174:175], v160 offset:0x200
	ds_read_b64_tr_b16 v[176:177], v160 offset:0xa00
	v_max_f32_e32 v137, v81, v81
	v_max_f32_e32 v138, v80, v80
	v_max_f32_e32 v137, v138, v137
	v_max3_f32 v137, v137, v82, v83
	v_max3_f32 v137, v137, v84, v85
	v_mfma_f32_32x32x16_bf16 v[48:63], v[144:147], v[182:185], v[48:63]
	ds_read_b64_tr_b16 v[182:183], v160 offset:0x1200
	ds_read_b64_tr_b16 v[184:185], v160 offset:0x1a00
	v_max3_f32 v137, v137, v86, v87
	v_max3_f32 v137, v137, v88, v89
	v_max3_f32 v137, v137, v90, v91
	v_max3_f32 v137, v137, v92, v93
	v_max3_f32 v137, v137, v94, v95
	v_mfma_f32_32x32x16_bf16 v[48:63], v[166:169], v[186:189], v[48:63]
	ds_read_b64_tr_b16 v[186:187], v160 offset:0x2200
	ds_read_b64_tr_b16 v[188:189], v160 offset:0x2a00
	v_max3_f32 v137, v137, v64, v65
	v_max3_f32 v137, v137, v66, v67
	v_max3_f32 v137, v137, v68, v69
	v_max3_f32 v137, v137, v70, v71
	v_max3_f32 v137, v137, v72, v73
	v_mfma_f32_32x32x16_bf16 v[48:63], v[170:173], v[212:215], v[48:63]
	ds_read_b64_tr_b16 v[212:213], v160 offset:0x3200
	ds_read_b64_tr_b16 v[214:215], v160 offset:0x3a00
	v_max3_f32 v137, v137, v74, v75
	v_max3_f32 v137, v137, v76, v77
	v_max3_f32 v137, v137, v78, v79
	v_mov_b32_e32 v138, v137
	s_nop 1
	v_permlane32_swap_b32_e32 v137, v138
	s_waitcnt lgkmcnt(0)
; #define SBAR() __builtin_amdgcn_sched_barrier(0)
; #define SWRITE(b, i) do { *(bf16x8*)(V_lds + (b) * SHM_V + vst0) = sr_[i].vs0;          \
;     *(bf16x8*)(V_lds + (b) * SHM_V + vst1) = sr_[i].vs1; int kc = sc * 2;               \
;     *(bf16x8*)(K_lds + (b) * SHM_K + KSWZ(sr, kc)) = sr_[i].ks0;                       \
;     *(bf16x8*)(K_lds + (b) * SHM_K + KSWZ(32 + sr, kc)) = sr_[i].ks1; } while (0)
; #define SWAIT() asm volatile("s_waitcnt vmcnt(0)" ::: "memory")
; #define RESC(a) do { if (__any((a) < 1.f)) { if (hi == 0) al_l[r32] = (a); asm volatile("s_waitcnt lgkmcnt(0)" ::: "memory"); \
;     _Pragma("unroll") for (int d = 0; d < 4; ++d) _Pragma("unroll") for (int r = 0; r < 16; ++r) o[d][r] *= al_l[crow(r, hi)]; } } while (0)
; __device__ __forceinline__ void partialSM(f32x16& p0, f32x16& p1, float& m_reg, float& mn, float& alpha) {
;     constexpr float C = SCALE * 1.4426950408889634f;
;     float pmax = p0[0];
; #pragma unroll
;     for (int r = 1; r < 16; ++r) pmax = fmaxf(pmax, p0[r]);
; #pragma unroll
;     for (int r = 0; r < 16; ++r) pmax = fmaxf(pmax, p1[r]);
;     { auto rr = __builtin_amdgcn_permlane32_swap(__float_as_uint(pmax), __float_as_uint(pmax), false, false);
;       pmax = fmaxf(__uint_as_float(rr[0]), __uint_as_float(rr[1])); }
;     if (__builtin_expect(__all(pmax - m_reg <= THR / SCALE), 1)) { mn = m_reg; alpha = 1.f; }
;     else { mn = fmaxf(m_reg, pmax); alpha = __builtin_amdgcn_exp2f((m_reg - mn) * C); m_reg = mn; }
;     const float mnC = -mn * C;
; #pragma unroll
;     for (int r = 0; r < 16; ++r) p0[r] = fmaf(p0[r], C, mnC);
; #pragma unroll
;     for (int r = 0; r < 16; ++r) p1[r] = fmaf(p1[r], C, mnC);
; #pragma unroll
;     for (int r = 0; r < 16; ++r) p0[r] = __builtin_amdgcn_exp2f(p0[r]);
; }
; __device__ __forceinline__ void attn_unit(const bf16_t* Qb, const bf16_t* Kh, const bf16_t* Vh, bf16_t* Ob, float* scr, int seq, float lam, float onemli, const float* subg, char* lds) {
;     ...
;             SLOAD(SO, (j + 1) * KVBLK); SBAR();
;             pv_d0(o, vb0, pa0, pa1, pa2, pa3); partialSM(pB0, pB1, m_reg, mnB, alB);
;             __syncthreads(); SWAIT(); SWRITE(0, SE);
;             RESC(alB); __syncthreads();
	v_mfma_f32_32x32x16_bf16 v[32:47], v[178:181], v[174:177], v[32:47]
	ds_read_b64_tr_b16 v[174:175], v160 offset:0x400
	ds_read_b64_tr_b16 v[176:177], v160 offset:0xc00
	v_max_f32_e32 v138, v138, v138
	v_max_f32_e32 v137, v137, v137
	v_max_f32_e32 v137, v137, v138
	v_sub_f32_e32 v138, v137, v134
	v_cmp_ge_f32_e32 vcc, s65, v138
	v_mfma_f32_32x32x16_bf16 v[32:47], v[144:147], v[182:185], v[32:47]
	ds_read_b64_tr_b16 v[182:183], v160 offset:0x1400
	ds_read_b64_tr_b16 v[184:185], v160 offset:0x1c00
	v_max_f32_e32 v138, v134, v134
	v_max_f32_e32 v137, v138, v137
	v_sub_f32_e32 v138, v134, v137
	v_mul_f32_e32 v138, 0x3e38aa3b, v138
	v_exp_f32_e32 v138, v138
	v_mfma_f32_32x32x16_bf16 v[32:47], v[166:169], v[186:189], v[32:47]
	ds_read_b64_tr_b16 v[186:187], v160 offset:0x2400
	ds_read_b64_tr_b16 v[188:189], v160 offset:0x2c00
	s_cmp_eq_u64 vcc, exec
	s_cselect_b64 s[8:9], -1, 0
	v_cndmask_b32_e64 v138, v138, 1.0, s[8:9]
	v_cndmask_b32_e64 v134, v137, v134, s[8:9]
	v_mul_f32_e32 v137, 0xbe38aa3b, v134
	v_mfma_f32_32x32x16_bf16 v[32:47], v[170:173], v[212:215], v[32:47]
	ds_read_b64_tr_b16 v[212:213], v160 offset:0x3400
	ds_read_b64_tr_b16 v[214:215], v160 offset:0x3c00
	v_fmamk_f32 v80, v80, 0x3e38aa3b, v137
	v_fmamk_f32 v81, v81, 0x3e38aa3b, v137
	v_fmamk_f32 v82, v82, 0x3e38aa3b, v137
	v_fmamk_f32 v83, v83, 0x3e38aa3b, v137
	v_fmamk_f32 v84, v84, 0x3e38aa3b, v137
	s_waitcnt lgkmcnt(0)
	v_mfma_f32_32x32x16_bf16 v[16:31], v[178:181], v[174:177], v[16:31]
	ds_read_b64_tr_b16 v[174:175], v160 offset:0x600
	ds_read_b64_tr_b16 v[176:177], v160 offset:0xe00
	v_fmamk_f32 v85, v85, 0x3e38aa3b, v137
	v_fmamk_f32 v86, v86, 0x3e38aa3b, v137
	v_fmamk_f32 v87, v87, 0x3e38aa3b, v137
	v_fmamk_f32 v88, v88, 0x3e38aa3b, v137
	v_fmamk_f32 v89, v89, 0x3e38aa3b, v137
	v_mfma_f32_32x32x16_bf16 v[16:31], v[144:147], v[182:185], v[16:31]
	ds_read_b64_tr_b16 v[182:183], v160 offset:0x1600
	ds_read_b64_tr_b16 v[184:185], v160 offset:0x1e00
	v_fmamk_f32 v90, v90, 0x3e38aa3b, v137
	v_fmamk_f32 v91, v91, 0x3e38aa3b, v137
	v_fmamk_f32 v92, v92, 0x3e38aa3b, v137
	v_fmamk_f32 v93, v93, 0x3e38aa3b, v137
	v_fmamk_f32 v94, v94, 0x3e38aa3b, v137
	v_mfma_f32_32x32x16_bf16 v[16:31], v[166:169], v[186:189], v[16:31]
	ds_read_b64_tr_b16 v[186:187], v160 offset:0x2600
	ds_read_b64_tr_b16 v[188:189], v160 offset:0x2e00
	v_fmamk_f32 v95, v95, 0x3e38aa3b, v137
	v_exp_f32_e32 v127, v80
	v_exp_f32_e32 v129, v81
	v_mfma_f32_32x32x16_bf16 v[16:31], v[170:173], v[212:215], v[16:31]
	ds_read_b64_tr_b16 v[212:213], v160 offset:0x3600
	ds_read_b64_tr_b16 v[214:215], v160 offset:0x3e00
	v_exp_f32_e32 v125, v82
	v_exp_f32_e32 v128, v83
	v_exp_f32_e32 v123, v84
	s_waitcnt lgkmcnt(0)
	v_mfma_f32_32x32x16_bf16 v[0:15], v[178:181], v[174:177], v[0:15]
	s_barrier
	s_waitcnt vmcnt(0)
	s_waitcnt vmcnt(3)
	ds_write_b128 v163, v[240:243]
	s_waitcnt vmcnt(1)
	ds_write_b128 v164, v[206:209]
	ds_write_b128 v161, v[244:247] offset:32768
	s_waitcnt vmcnt(0)
	ds_write_b128 v162, v[248:251] offset:32768
	v_exp_f32_e32 v126, v85
	v_exp_f32_e32 v122, v86
	v_exp_f32_e32 v124, v87
	v_mfma_f32_32x32x16_bf16 v[0:15], v[144:147], v[182:185], v[0:15]
	v_exp_f32_e32 v119, v88
	v_exp_f32_e32 v121, v89
	v_exp_f32_e32 v117, v90
	v_mfma_f32_32x32x16_bf16 v[0:15], v[166:169], v[186:189], v[0:15]
	v_exp_f32_e32 v120, v91
	v_exp_f32_e32 v115, v92
	v_exp_f32_e32 v118, v93
	v_mfma_f32_32x32x16_bf16 v[0:15], v[170:173], v[212:215], v[0:15]
	v_exp_f32_e32 v114, v94
	v_exp_f32_e32 v116, v95
	v_cmp_gt_f32_e32 vcc, 1.0, v138
	s_cbranch_vccz .LBB0_284
	s_and_saveexec_b64 s[2:3], s[6:7]
	ds_write_b32 v157, v138 offset:128
	s_or_b64 exec, exec, s[2:3]
	s_waitcnt lgkmcnt(0)
	ds_read_b128 v[240:243], v158 offset:224
	ds_read_b128 v[244:247], v158 offset:192
	ds_read_b128 v[248:251], v158 offset:160
	ds_read_b128 v[206:209], v158 offset:128
	s_waitcnt lgkmcnt(3)
	v_pk_mul_f32 v[62:63], v[62:63], v[242:243]
	s_waitcnt lgkmcnt(2)
	v_pk_mul_f32 v[58:59], v[58:59], v[246:247]
	s_waitcnt lgkmcnt(1)
	v_pk_mul_f32 v[54:55], v[54:55], v[250:251]
	s_waitcnt lgkmcnt(0)
	v_pk_mul_f32 v[50:51], v[50:51], v[208:209]
	v_pk_mul_f32 v[60:61], v[60:61], v[240:241]
	v_pk_mul_f32 v[56:57], v[56:57], v[244:245]
	v_pk_mul_f32 v[52:53], v[52:53], v[248:249]
	v_pk_mul_f32 v[48:49], v[48:49], v[206:207]
	v_pk_mul_f32 v[46:47], v[46:47], v[242:243]
	v_pk_mul_f32 v[42:43], v[42:43], v[246:247]
	v_pk_mul_f32 v[38:39], v[38:39], v[250:251]
	v_pk_mul_f32 v[34:35], v[34:35], v[208:209]
	v_pk_mul_f32 v[44:45], v[44:45], v[240:241]
	v_pk_mul_f32 v[40:41], v[40:41], v[244:245]
	v_pk_mul_f32 v[36:37], v[36:37], v[248:249]
	v_pk_mul_f32 v[32:33], v[32:33], v[206:207]
	v_pk_mul_f32 v[30:31], v[30:31], v[242:243]
	v_pk_mul_f32 v[26:27], v[26:27], v[246:247]
	v_pk_mul_f32 v[22:23], v[22:23], v[250:251]
	v_pk_mul_f32 v[18:19], v[18:19], v[208:209]
	v_pk_mul_f32 v[28:29], v[28:29], v[240:241]
	v_pk_mul_f32 v[24:25], v[24:25], v[244:245]
	v_pk_mul_f32 v[20:21], v[20:21], v[248:249]
	v_pk_mul_f32 v[16:17], v[16:17], v[206:207]
	v_pk_mul_f32 v[14:15], v[14:15], v[242:243]
	v_pk_mul_f32 v[10:11], v[10:11], v[246:247]
	v_pk_mul_f32 v[6:7], v[6:7], v[250:251]
	v_pk_mul_f32 v[2:3], v[2:3], v[208:209]
	v_pk_mul_f32 v[12:13], v[12:13], v[240:241]
	v_pk_mul_f32 v[8:9], v[8:9], v[244:245]
	v_pk_mul_f32 v[4:5], v[4:5], v[248:249]
	v_pk_mul_f32 v[0:1], v[0:1], v[206:207]
; #define SBAR() __builtin_amdgcn_sched_barrier(0)
; #define RESC(a) do { if (__any((a) < 1.f)) { if (hi == 0) al_l[r32] = (a); asm volatile("s_waitcnt lgkmcnt(0)" ::: "memory"); \
;     _Pragma("unroll") for (int d = 0; d < 4; ++d) _Pragma("unroll") for (int r = 0; r < 16; ++r) o[d][r] *= al_l[crow(r, hi)]; } } while (0)
; __device__ __forceinline__ void finishSM(f32x16& p0, f32x16& p1, float alpha, float& l_reg, bf16x8& pa0, bf16x8& pa1, bf16x8& pa2, bf16x8& pa3) {
; #pragma unroll
;     for (int r = 0; r < 16; ++r) p1[r] = __builtin_amdgcn_exp2f(p1[r]);
;     float ps = 0;
; #pragma unroll
;     for (int r = 0; r < 16; ++r) ps += p0[r];
; #pragma unroll
;     for (int r = 0; r < 16; ++r) ps += p1[r];
;     { auto rr = __builtin_amdgcn_permlane32_swap(__float_as_uint(ps), __float_as_uint(ps), false, false);
;       ps = __uint_as_float(rr[0]) + __uint_as_float(rr[1]); }
;     l_reg = l_reg * alpha + ps;
;     ...
;     PK4(p0, 0, pa0); PK4(p0, 8, pa1); PK4(p1, 0, pa2); PK4(p1, 8, pa3);
;     ...
; }
; __device__ __forceinline__ void attn_unit(const bf16_t* Qb, const bf16_t* Kh, const bf16_t* Vh, bf16_t* Ob, float* scr, int seq, float lam, float onemli, const float* subg, char* lds) {
;     ...
;             RESC(alB); __syncthreads();
;             SBAR(); qkt(pA0, pA1, K_lds, qr, r32, hi, comp);
;             finishSM(pB0, pB1, alB, l_reg, pa0, pa1, pa2, pa3); SBAR();
;             SLOAD(SE, (j + 2) * KVBLK); SBAR();
;             pv_d0(o, vb0 + (int)SHM_V, pa0, pa1, pa2, pa3); partialSM(pA0, pA1, m_reg, mnA, alA);
.LBB0_284:
	v_fmamk_f32 v167, v64, 0x3e38aa3b, v137
	v_fmamk_f32 v168, v65, 0x3e38aa3b, v137
	v_fmamk_f32 v169, v66, 0x3e38aa3b, v137
	v_fmamk_f32 v170, v67, 0x3e38aa3b, v137
	v_fmamk_f32 v171, v68, 0x3e38aa3b, v137
	v_fmamk_f32 v144, v69, 0x3e38aa3b, v137
	v_fmamk_f32 v145, v70, 0x3e38aa3b, v137
	v_fmamk_f32 v146, v71, 0x3e38aa3b, v137
	v_fmamk_f32 v147, v72, 0x3e38aa3b, v137
	v_fmamk_f32 v148, v73, 0x3e38aa3b, v137
	v_fmamk_f32 v149, v74, 0x3e38aa3b, v137
	v_fmamk_f32 v166, v75, 0x3e38aa3b, v137
	v_fmamk_f32 v139, v76, 0x3e38aa3b, v137
	v_fmamk_f32 v172, v77, 0x3e38aa3b, v137
	v_fmamk_f32 v173, v78, 0x3e38aa3b, v137
	v_fmac_f32_e32 v137, 0x3e38aa3b, v79
	s_waitcnt lgkmcnt(0)
	s_barrier
	ds_read_b128 v[64:67], v140 offset:32768
	ds_read_b128 v[68:71], v140 offset:40960
	ds_read_b128 v[174:177], v143 offset:32768
	ds_read_b128 v[178:181], v143 offset:40960
	v_exp_f32_e32 v185, v139
	v_add_f32_e32 v139, 0, v127
	s_waitcnt lgkmcnt(3)
	v_mfma_f32_32x32x16_bf16 v[80:95], v[64:67], v[110:113], 0
	v_add_f32_e32 v139, v129, v139
	v_add_f32_e32 v139, v125, v139
	v_add_f32_e32 v139, v128, v139
	v_add_f32_e32 v139, v123, v139
	v_add_f32_e32 v139, v126, v139
	v_add_f32_e32 v139, v122, v139
	v_add_f32_e32 v139, v124, v139
	s_waitcnt lgkmcnt(2)
	v_mfma_f32_32x32x16_bf16 v[64:79], v[68:71], v[110:113], 0
	v_add_f32_e32 v139, v119, v139
	v_add_f32_e32 v139, v121, v139
	v_add_f32_e32 v139, v117, v139
	v_add_f32_e32 v139, v120, v139
	v_add_f32_e32 v139, v115, v139
	v_add_f32_e32 v139, v118, v139
	v_add_f32_e32 v139, v114, v139
	s_waitcnt lgkmcnt(1)
	v_mfma_f32_32x32x16_bf16 v[80:95], v[174:177], v[106:109], v[80:95]
	v_add_f32_e32 v139, v116, v139
	v_exp_f32_e32 v145, v145
	v_exp_f32_e32 v182, v148
	v_exp_f32_e32 v183, v149
	v_exp_f32_e32 v184, v166
	v_exp_f32_e32 v186, v172
	v_exp_f32_e32 v187, v173
	s_waitcnt lgkmcnt(0)
	v_mfma_f32_32x32x16_bf16 v[64:79], v[178:181], v[106:109], v[64:79]
	ds_read_b128 v[174:177], v142 offset:32768
	ds_read_b128 v[178:181], v142 offset:40960
	v_exp_f32_e32 v137, v137
	s_waitcnt lgkmcnt(1)
	v_mfma_f32_32x32x16_bf16 v[80:95], v[174:177], v[102:105], v[80:95]
	s_waitcnt lgkmcnt(0)
	v_mfma_f32_32x32x16_bf16 v[64:79], v[178:181], v[102:105], v[64:79]
	ds_read_b128 v[174:177], v141 offset:32768
	ds_read_b128 v[178:181], v141 offset:40960
	s_waitcnt lgkmcnt(1)
	v_mfma_f32_32x32x16_bf16 v[80:95], v[174:177], v[98:101], v[80:95]
	v_exp_f32_e32 v174, v167
	v_exp_f32_e32 v175, v168
	v_exp_f32_e32 v176, v169
	v_exp_f32_e32 v177, v170
	v_add_f32_e32 v139, v174, v139
	v_add_f32_e32 v139, v175, v139
	v_add_f32_e32 v139, v176, v139
	s_waitcnt lgkmcnt(0)
	v_mfma_f32_32x32x16_bf16 v[64:79], v[178:181], v[98:101], v[64:79]
	v_exp_f32_e32 v178, v171
	v_exp_f32_e32 v179, v144
	v_exp_f32_e32 v180, v146
	v_add_f32_e32 v139, v177, v139
	v_exp_f32_e32 v181, v147
	v_add_f32_e32 v139, v178, v139
	v_add_f32_e32 v139, v179, v139
	v_add_f32_e32 v139, v145, v139
	v_add_f32_e32 v139, v180, v139
	v_add_f32_e32 v139, v181, v139
	v_add_f32_e32 v139, v182, v139
	v_add_f32_e32 v139, v183, v139
	v_add_f32_e32 v139, v184, v139
	v_add_f32_e32 v139, v185, v139
	v_add_f32_e32 v139, v186, v139
	v_add_f32_e32 v139, v187, v139
	v_add_f32_e32 v139, v137, v139
	v_mov_b32_e32 v144, v139
	s_nop 1
	v_permlane32_swap_b32_e32 v139, v144
	v_cvt_pk_bf16_f32 v146, v127, v129
	v_cvt_pk_bf16_f32 v147, v125, v128
	v_cvt_pk_bf16_f32 v148, v123, v126
	v_cvt_pk_bf16_f32 v149, v122, v124
	v_cvt_pk_bf16_f32 v166, v119, v121
	v_cvt_pk_bf16_f32 v167, v117, v120
	v_cvt_pk_bf16_f32 v168, v115, v118
	v_cvt_pk_bf16_f32 v169, v114, v116
	v_cvt_pk_bf16_f32 v170, v174, v175
	v_cvt_pk_bf16_f32 v171, v176, v177
	v_cvt_pk_bf16_f32 v172, v178, v179
	v_cvt_pk_bf16_f32 v173, v145, v180
	v_cvt_pk_bf16_f32 v174, v181, v182
	v_cvt_pk_bf16_f32 v175, v183, v184
	v_cvt_pk_bf16_f32 v176, v185, v186
	v_cvt_pk_bf16_f32 v177, v187, v137
	s_nop 0
	v_permlane32_swap_b32_e32 v146, v148
	v_permlane32_swap_b32_e32 v147, v149
	v_permlane32_swap_b32_e32 v166, v168
	v_permlane32_swap_b32_e32 v167, v169
	v_permlane32_swap_b32_e32 v170, v172
	v_permlane32_swap_b32_e32 v171, v173
	v_permlane32_swap_b32_e32 v174, v176
	v_permlane32_swap_b32_e32 v175, v177
	v_add_u32_e32 v118, 0x20000, v96
	v_add_u32_e32 v122, 0x30000, v96
	global_load_dwordx4 v[114:117], v118, s[58:59]
	s_nop 0
	global_load_dwordx4 v[118:121], v118, s[28:29]
	s_nop 0
	global_load_dwordx4 v[126:129], v122, s[58:59]
	s_nop 0
	global_load_dwordx4 v[122:125], v122, s[28:29]
	ds_read_b64_tr_b16 v[178:179], v159 offset:0
	ds_read_b64_tr_b16 v[180:181], v159 offset:0x800
	ds_read_b64_tr_b16 v[182:183], v159 offset:0x1000
	ds_read_b64_tr_b16 v[184:185], v159 offset:0x1800
	ds_read_b64_tr_b16 v[186:187], v159 offset:0x2000
	ds_read_b64_tr_b16 v[188:189], v159 offset:0x2800
	ds_read_b64_tr_b16 v[212:213], v159 offset:0x3000
	ds_read_b64_tr_b16 v[214:215], v159 offset:0x3800
	s_waitcnt lgkmcnt(0)
	s_nop 0
	v_mfma_f32_32x32x16_bf16 v[48:63], v[146:149], v[178:181], v[48:63]
	ds_read_b64_tr_b16 v[178:179], v159 offset:0x200
	ds_read_b64_tr_b16 v[180:181], v159 offset:0xa00
	v_max_f32_e32 v255, v81, v81
	v_max_f32_e32 v210, v80, v80
	v_max_f32_e32 v255, v210, v255
	v_max3_f32 v255, v255, v82, v83
	v_max3_f32 v255, v255, v84, v85
	v_mfma_f32_32x32x16_bf16 v[48:63], v[166:169], v[182:185], v[48:63]
	ds_read_b64_tr_b16 v[182:183], v159 offset:0x1200
	ds_read_b64_tr_b16 v[184:185], v159 offset:0x1a00
	v_max3_f32 v255, v255, v86, v87
	v_max3_f32 v255, v255, v88, v89
	v_max3_f32 v255, v255, v90, v91
	v_max3_f32 v255, v255, v92, v93
	v_max3_f32 v255, v255, v94, v95
	v_mfma_f32_32x32x16_bf16 v[48:63], v[170:173], v[186:189], v[48:63]
	ds_read_b64_tr_b16 v[186:187], v159 offset:0x2200
	ds_read_b64_tr_b16 v[188:189], v159 offset:0x2a00
	v_max3_f32 v255, v255, v64, v65
	v_max3_f32 v255, v255, v66, v67
	v_max3_f32 v255, v255, v68, v69
	v_max3_f32 v255, v255, v70, v71
	v_max3_f32 v255, v255, v72, v73
	v_mfma_f32_32x32x16_bf16 v[48:63], v[174:177], v[212:215], v[48:63]
	ds_read_b64_tr_b16 v[212:213], v159 offset:0x3200
	ds_read_b64_tr_b16 v[214:215], v159 offset:0x3a00
	v_max3_f32 v255, v255, v74, v75
	v_max3_f32 v255, v255, v76, v77
	v_max3_f32 v255, v255, v78, v79
	v_mov_b32_e32 v210, v255
	s_nop 1
	v_permlane32_swap_b32_e32 v255, v210
	s_waitcnt lgkmcnt(0)
; #define SWRITE(b, i) do { *(bf16x8*)(V_lds + (b) * SHM_V + vst0) = sr_[i].vs0;          \
;     *(bf16x8*)(V_lds + (b) * SHM_V + vst1) = sr_[i].vs1; int kc = sc * 2;               \
;     *(bf16x8*)(K_lds + (b) * SHM_K + KSWZ(sr, kc)) = sr_[i].ks0;                       \
;     *(bf16x8*)(K_lds + (b) * SHM_K + KSWZ(32 + sr, kc)) = sr_[i].ks1; } while (0)
; #define SWAIT() asm volatile("s_waitcnt vmcnt(0)" ::: "memory")
; #define RESC(a) do { if (__any((a) < 1.f)) { if (hi == 0) al_l[r32] = (a); asm volatile("s_waitcnt lgkmcnt(0)" ::: "memory"); \
;     _Pragma("unroll") for (int d = 0; d < 4; ++d) _Pragma("unroll") for (int r = 0; r < 16; ++r) o[d][r] *= al_l[crow(r, hi)]; } } while (0)
; __device__ __forceinline__ void partialSM(f32x16& p0, f32x16& p1, float& m_reg, float& mn, float& alpha) {
;     constexpr float C = SCALE * 1.4426950408889634f;
;     float pmax = p0[0];
; #pragma unroll
;     for (int r = 1; r < 16; ++r) pmax = fmaxf(pmax, p0[r]);
; #pragma unroll
;     for (int r = 0; r < 16; ++r) pmax = fmaxf(pmax, p1[r]);
;     { auto rr = __builtin_amdgcn_permlane32_swap(__float_as_uint(pmax), __float_as_uint(pmax), false, false);
;       pmax = fmaxf(__uint_as_float(rr[0]), __uint_as_float(rr[1])); }
;     if (__builtin_expect(__all(pmax - m_reg <= THR / SCALE), 1)) { mn = m_reg; alpha = 1.f; }
;     else { mn = fmaxf(m_reg, pmax); alpha = __builtin_amdgcn_exp2f((m_reg - mn) * C); m_reg = mn; }
;     const float mnC = -mn * C;
; #pragma unroll
;     for (int r = 0; r < 16; ++r) p0[r] = fmaf(p0[r], C, mnC);
; #pragma unroll
;     for (int r = 0; r < 16; ++r) p1[r] = fmaf(p1[r], C, mnC);
; #pragma unroll
;     for (int r = 0; r < 16; ++r) p0[r] = __builtin_amdgcn_exp2f(p0[r]);
; }
; __device__ __forceinline__ void attn_unit(const bf16_t* Qb, const bf16_t* Kh, const bf16_t* Vh, bf16_t* Ob, float* scr, int seq, float lam, float onemli, const float* subg, char* lds) {
;     ...
;             pv_d0(o, vb0 + (int)SHM_V, pa0, pa1, pa2, pa3); partialSM(pA0, pA1, m_reg, mnA, alA);
;             __syncthreads(); SWAIT(); SWRITE(1, SO);
;             RESC(alA); __syncthreads();
	v_mfma_f32_32x32x16_bf16 v[32:47], v[146:149], v[178:181], v[32:47]
	ds_read_b64_tr_b16 v[178:179], v159 offset:0x400
	ds_read_b64_tr_b16 v[180:181], v159 offset:0xc00
	v_max_f32_e32 v210, v210, v210
	v_max_f32_e32 v255, v255, v255
	v_max_f32_e32 v255, v255, v210
	v_sub_f32_e32 v210, v255, v134
	v_cmp_ge_f32_e32 vcc, s65, v210
	v_mfma_f32_32x32x16_bf16 v[32:47], v[166:169], v[182:185], v[32:47]
	ds_read_b64_tr_b16 v[182:183], v159 offset:0x1400
	ds_read_b64_tr_b16 v[184:185], v159 offset:0x1c00
	v_max_f32_e32 v210, v134, v134
	v_max_f32_e32 v210, v210, v255
	v_sub_f32_e32 v255, v134, v210
	v_mul_f32_e32 v255, 0x3e38aa3b, v255
	v_exp_f32_e32 v255, v255
	v_mfma_f32_32x32x16_bf16 v[32:47], v[170:173], v[186:189], v[32:47]
	ds_read_b64_tr_b16 v[186:187], v159 offset:0x2400
	ds_read_b64_tr_b16 v[188:189], v159 offset:0x2c00
	s_cmp_eq_u64 vcc, exec
	s_cselect_b64 s[8:9], -1, 0
	v_cndmask_b32_e64 v255, v255, 1.0, s[8:9]
	v_cndmask_b32_e64 v134, v210, v134, s[8:9]
	v_mul_f32_e32 v210, 0xbe38aa3b, v134
	v_mfma_f32_32x32x16_bf16 v[32:47], v[174:177], v[212:215], v[32:47]
	ds_read_b64_tr_b16 v[212:213], v159 offset:0x3400
	ds_read_b64_tr_b16 v[214:215], v159 offset:0x3c00
	v_fmamk_f32 v80, v80, 0x3e38aa3b, v210
	v_fmamk_f32 v81, v81, 0x3e38aa3b, v210
	v_fmamk_f32 v82, v82, 0x3e38aa3b, v210
	v_fmamk_f32 v83, v83, 0x3e38aa3b, v210
	v_fmamk_f32 v84, v84, 0x3e38aa3b, v210
	s_waitcnt lgkmcnt(0)
	v_mfma_f32_32x32x16_bf16 v[16:31], v[146:149], v[178:181], v[16:31]
	ds_read_b64_tr_b16 v[178:179], v159 offset:0x600
	ds_read_b64_tr_b16 v[180:181], v159 offset:0xe00
	v_fmamk_f32 v85, v85, 0x3e38aa3b, v210
	v_fmamk_f32 v86, v86, 0x3e38aa3b, v210
	v_fmamk_f32 v87, v87, 0x3e38aa3b, v210
	v_fmamk_f32 v88, v88, 0x3e38aa3b, v210
	v_fmamk_f32 v89, v89, 0x3e38aa3b, v210
	v_mfma_f32_32x32x16_bf16 v[16:31], v[166:169], v[182:185], v[16:31]
	ds_read_b64_tr_b16 v[182:183], v159 offset:0x1600
	ds_read_b64_tr_b16 v[184:185], v159 offset:0x1e00
	v_fmamk_f32 v90, v90, 0x3e38aa3b, v210
	v_fmamk_f32 v91, v91, 0x3e38aa3b, v210
	v_fmamk_f32 v92, v92, 0x3e38aa3b, v210
	v_fmamk_f32 v93, v93, 0x3e38aa3b, v210
	v_fmamk_f32 v94, v94, 0x3e38aa3b, v210
	v_mfma_f32_32x32x16_bf16 v[16:31], v[170:173], v[186:189], v[16:31]
	ds_read_b64_tr_b16 v[186:187], v159 offset:0x2600
	ds_read_b64_tr_b16 v[188:189], v159 offset:0x2e00
	v_fmamk_f32 v95, v95, 0x3e38aa3b, v210
	v_exp_f32_e32 v240, v80
	v_exp_f32_e32 v241, v81
	v_mfma_f32_32x32x16_bf16 v[16:31], v[174:177], v[212:215], v[16:31]
	ds_read_b64_tr_b16 v[212:213], v159 offset:0x3600
	ds_read_b64_tr_b16 v[214:215], v159 offset:0x3e00
	v_exp_f32_e32 v242, v82
	v_exp_f32_e32 v243, v83
	v_exp_f32_e32 v244, v84
	s_waitcnt lgkmcnt(0)
	v_mfma_f32_32x32x16_bf16 v[0:15], v[146:149], v[178:181], v[0:15]
	s_barrier
	s_waitcnt vmcnt(0)
	s_waitcnt vmcnt(3)
	ds_write_b128 v163, v[114:117] offset:16384
	s_waitcnt vmcnt(1)
	ds_write_b128 v164, v[126:129] offset:16384
	ds_write_b128 v161, v[118:121] offset:49152
	s_waitcnt vmcnt(0)
	ds_write_b128 v162, v[122:125] offset:49152
	v_exp_f32_e32 v245, v85
	v_exp_f32_e32 v246, v86
	v_exp_f32_e32 v247, v87
	v_mfma_f32_32x32x16_bf16 v[0:15], v[166:169], v[182:185], v[0:15]
	v_exp_f32_e32 v248, v88
	v_exp_f32_e32 v249, v89
	v_exp_f32_e32 v250, v90
	v_mfma_f32_32x32x16_bf16 v[0:15], v[170:173], v[186:189], v[0:15]
	v_exp_f32_e32 v251, v91
	v_exp_f32_e32 v206, v92
	v_exp_f32_e32 v207, v93
	v_mfma_f32_32x32x16_bf16 v[0:15], v[174:177], v[212:215], v[0:15]
	v_exp_f32_e32 v208, v94
	v_exp_f32_e32 v209, v95
	v_mov_b32_e32 v137, v255
	v_cmp_gt_f32_e32 vcc, 1.0, v137
	s_cbranch_vccz .LBB0_288
	s_and_saveexec_b64 s[2:3], s[6:7]
	ds_write_b32 v157, v137 offset:128
	s_or_b64 exec, exec, s[2:3]
	s_waitcnt lgkmcnt(0)
	ds_read_b128 v[114:117], v158 offset:224
	ds_read_b128 v[118:121], v158 offset:192
	ds_read_b128 v[122:125], v158 offset:160
	ds_read_b128 v[126:129], v158 offset:128
	s_waitcnt lgkmcnt(3)
	v_pk_mul_f32 v[62:63], v[62:63], v[116:117]
	s_waitcnt lgkmcnt(2)
	v_pk_mul_f32 v[58:59], v[58:59], v[120:121]
	s_waitcnt lgkmcnt(1)
	v_pk_mul_f32 v[54:55], v[54:55], v[124:125]
	s_waitcnt lgkmcnt(0)
	v_pk_mul_f32 v[50:51], v[50:51], v[128:129]
	v_pk_mul_f32 v[60:61], v[60:61], v[114:115]
	v_pk_mul_f32 v[56:57], v[56:57], v[118:119]
	v_pk_mul_f32 v[52:53], v[52:53], v[122:123]
	v_pk_mul_f32 v[48:49], v[48:49], v[126:127]
	v_pk_mul_f32 v[46:47], v[46:47], v[116:117]
	v_pk_mul_f32 v[42:43], v[42:43], v[120:121]
	v_pk_mul_f32 v[38:39], v[38:39], v[124:125]
	v_pk_mul_f32 v[34:35], v[34:35], v[128:129]
	v_pk_mul_f32 v[44:45], v[44:45], v[114:115]
	v_pk_mul_f32 v[40:41], v[40:41], v[118:119]
	v_pk_mul_f32 v[36:37], v[36:37], v[122:123]
	v_pk_mul_f32 v[32:33], v[32:33], v[126:127]
	v_pk_mul_f32 v[30:31], v[30:31], v[116:117]
	v_pk_mul_f32 v[26:27], v[26:27], v[120:121]
	v_pk_mul_f32 v[22:23], v[22:23], v[124:125]
	v_pk_mul_f32 v[18:19], v[18:19], v[128:129]
	v_pk_mul_f32 v[28:29], v[28:29], v[114:115]
	v_pk_mul_f32 v[24:25], v[24:25], v[118:119]
	v_pk_mul_f32 v[20:21], v[20:21], v[122:123]
	v_pk_mul_f32 v[16:17], v[16:17], v[126:127]
	v_pk_mul_f32 v[14:15], v[14:15], v[116:117]
	v_pk_mul_f32 v[10:11], v[10:11], v[120:121]
	v_pk_mul_f32 v[6:7], v[6:7], v[124:125]
	v_pk_mul_f32 v[2:3], v[2:3], v[128:129]
	v_pk_mul_f32 v[12:13], v[12:13], v[114:115]
	v_pk_mul_f32 v[8:9], v[8:9], v[118:119]
	v_pk_mul_f32 v[4:5], v[4:5], v[122:123]
	v_pk_mul_f32 v[0:1], v[0:1], v[126:127]
; #define SBAR() __builtin_amdgcn_sched_barrier(0)
; #define RESC(a) do { if (__any((a) < 1.f)) { if (hi == 0) al_l[r32] = (a); asm volatile("s_waitcnt lgkmcnt(0)" ::: "memory"); \
;     _Pragma("unroll") for (int d = 0; d < 4; ++d) _Pragma("unroll") for (int r = 0; r < 16; ++r) o[d][r] *= al_l[crow(r, hi)]; } } while (0)
; __device__ __forceinline__ void partialSM(f32x16& p0, f32x16& p1, float& m_reg, float& mn, float& alpha) {
;     ...
; #pragma unroll
;     for (int r = 0; r < 16; ++r) p0[r] = fmaf(p0[r], C, mnC);
; #pragma unroll
;     for (int r = 0; r < 16; ++r) p1[r] = fmaf(p1[r], C, mnC);
; #pragma unroll
;     for (int r = 0; r < 16; ++r) p0[r] = __builtin_amdgcn_exp2f(p0[r]);
; }
; __device__ __forceinline__ void finishSM(f32x16& p0, f32x16& p1, float alpha, float& l_reg, bf16x8& pa0, bf16x8& pa1, bf16x8& pa2, bf16x8& pa3) {
; #pragma unroll
;     for (int r = 0; r < 16; ++r) p1[r] = __builtin_amdgcn_exp2f(p1[r]);
;     float ps = 0;
; #pragma unroll
;     for (int r = 0; r < 16; ++r) ps += p0[r];
; #pragma unroll
;     for (int r = 0; r < 16; ++r) ps += p1[r];
;     { auto rr = __builtin_amdgcn_permlane32_swap(__float_as_uint(ps), __float_as_uint(ps), false, false);
;       ps = __uint_as_float(rr[0]) + __uint_as_float(rr[1]); }
;     l_reg = l_reg * alpha + ps;
; __device__ __forceinline__ void attn_unit(const bf16_t* Qb, const bf16_t* Kh, const bf16_t* Vh, bf16_t* Ob, float* scr, int seq, float lam, float onemli, const float* subg, char* lds) {
;     ...
;             RESC(alA); __syncthreads();
;         }
;         SBAR(); qkt(pB0, pB1, K_lds + SHM_K, qr, r32, hi, comp);
;         finishSM(pA0, pA1, alA, l_reg, pa0, pa1, pa2, pa3); SBAR();
;         pv_d0(o, vb0, pa0, pa1, pa2, pa3); partialSM(pB0, pB1, m_reg, mnB, alB);
.LBB0_288:
	v_mov_b32_e32 v114, v210
	v_pk_fma_f32 v[128:129], v[64:65], s[72:73], v[114:115] op_sel_hi:[1,0,0]
	v_add_f32_e32 v64, v135, v136
	v_fmac_f32_e32 v64, v133, v132
	v_add_f32_e32 v132, v139, v144
	s_add_i32 s36, s36, 2
	v_pk_fma_f32 v[126:127], v[66:67], s[72:73], v[114:115] op_sel_hi:[1,0,0]
	v_pk_fma_f32 v[122:123], v[68:69], s[72:73], v[114:115] op_sel_hi:[1,0,0]
	v_pk_fma_f32 v[118:119], v[70:71], s[72:73], v[114:115] op_sel_hi:[1,0,0]
	v_pk_fma_f32 v[116:117], v[72:73], s[72:73], v[114:115] op_sel_hi:[1,0,0]
	v_pk_fma_f32 v[124:125], v[74:75], s[72:73], v[114:115] op_sel_hi:[1,0,0]
	v_pk_fma_f32 v[120:121], v[76:77], s[72:73], v[114:115] op_sel_hi:[1,0,0]
	v_pk_fma_f32 v[114:115], v[78:79], s[72:73], v[114:115] op_sel_hi:[1,0,0]
	v_fmac_f32_e32 v132, v64, v138
	s_cmp_lt_u32 s36, s67
	v_add_u32_e32 v96, 0x40000, v96
	s_waitcnt lgkmcnt(0)
	s_barrier
	s_cbranch_scc0 .LBB0_290
	v_mov_b32_e32 v133, v137
	s_branch .LBB0_280
.LBB0_290:
	v_mov_b32_e32 v169, v240
	v_mov_b32_e32 v173, v241
	v_mov_b32_e32 v170, v242
	v_mov_b32_e32 v174, v243
	v_mov_b32_e32 v171, v244
	v_mov_b32_e32 v175, v245
	v_mov_b32_e32 v172, v246
	v_mov_b32_e32 v176, v247
	v_mov_b32_e32 v145, v248
	v_mov_b32_e32 v149, v249
	v_mov_b32_e32 v146, v250
	v_mov_b32_e32 v166, v251
	v_mov_b32_e32 v147, v206
	v_mov_b32_e32 v167, v207
	v_mov_b32_e32 v148, v208
	v_mov_b32_e32 v168, v209
	ds_read_b128 v[64:67], v140 offset:49152
	ds_read_b128 v[68:71], v140 offset:57344
	v_add_f32_e32 v96, 0, v169
	v_add_f32_e32 v96, v173, v96
	v_add_f32_e32 v96, v170, v96
	s_waitcnt lgkmcnt(1)
	v_mfma_f32_32x32x16_bf16 v[80:95], v[64:67], v[110:113], 0
	v_add_f32_e32 v96, v174, v96
	v_add_f32_e32 v96, v171, v96
	v_add_f32_e32 v96, v175, v96
	v_add_f32_e32 v96, v172, v96
	v_add_f32_e32 v96, v176, v96
	v_add_f32_e32 v96, v145, v96
	v_add_f32_e32 v96, v149, v96
	s_waitcnt lgkmcnt(0)
	v_mfma_f32_32x32x16_bf16 v[64:79], v[68:71], v[110:113], 0
	ds_read_b128 v[110:113], v143 offset:49152
	ds_read_b128 v[178:181], v143 offset:57344
	v_add_f32_e32 v96, v146, v96
	v_add_f32_e32 v96, v166, v96
	v_add_f32_e32 v96, v147, v96
	v_add_f32_e32 v96, v167, v96
	v_add_f32_e32 v96, v148, v96
	v_add_f32_e32 v96, v168, v96
	s_waitcnt lgkmcnt(1)
	v_mfma_f32_32x32x16_bf16 v[80:95], v[110:113], v[106:109], v[80:95]
	v_exp_f32_e32 v116, v116
	v_exp_f32_e32 v117, v117
	v_exp_f32_e32 v120, v120
	v_exp_f32_e32 v121, v121
	v_exp_f32_e32 v115, v115
	s_waitcnt lgkmcnt(0)
	v_mfma_f32_32x32x16_bf16 v[64:79], v[178:181], v[106:109], v[64:79]
	ds_read_b128 v[106:109], v142 offset:49152
	ds_read_b128 v[110:113], v142 offset:57344
	s_waitcnt lgkmcnt(1)
	v_mfma_f32_32x32x16_bf16 v[80:95], v[106:109], v[102:105], v[80:95]
	s_waitcnt lgkmcnt(0)
	v_mfma_f32_32x32x16_bf16 v[64:79], v[110:113], v[102:105], v[64:79]
	ds_read_b128 v[102:105], v141 offset:49152
	ds_read_b128 v[106:109], v141 offset:57344
	v_exp_f32_e32 v110, v127
	v_exp_f32_e32 v111, v122
	v_exp_f32_e32 v112, v123
	v_exp_f32_e32 v113, v118
	v_exp_f32_e32 v118, v119
	v_exp_f32_e32 v119, v124
	s_waitcnt lgkmcnt(1)
	v_mfma_f32_32x32x16_bf16 v[80:95], v[102:105], v[98:101], v[80:95]
	v_exp_f32_e32 v122, v125
	v_exp_f32_e32 v123, v114
	s_waitcnt lgkmcnt(0)
	v_mfma_f32_32x32x16_bf16 v[64:79], v[106:109], v[98:101], v[64:79]
	v_exp_f32_e32 v99, v128
	v_exp_f32_e32 v108, v129
	v_exp_f32_e32 v109, v126
	v_cvt_pk_bf16_f32 v100, v169, v173
	v_add_f32_e32 v96, v99, v96
	v_add_f32_e32 v96, v108, v96
	v_add_f32_e32 v96, v109, v96
	v_add_f32_e32 v96, v110, v96
	v_add_f32_e32 v96, v111, v96
	v_add_f32_e32 v96, v112, v96
	v_add_f32_e32 v96, v113, v96
	v_add_f32_e32 v96, v118, v96
	v_add_f32_e32 v96, v116, v96
	v_add_f32_e32 v96, v117, v96
	v_add_f32_e32 v96, v119, v96
	v_add_f32_e32 v96, v122, v96
	v_add_f32_e32 v96, v120, v96
	v_add_f32_e32 v96, v121, v96
	v_add_f32_e32 v96, v123, v96
	v_add_f32_e32 v96, v115, v96
	v_mov_b32_e32 v98, v96
	v_cvt_pk_bf16_f32 v101, v170, v174
	v_cvt_pk_bf16_f32 v102, v171, v175
	s_nop 1
	v_permlane32_swap_b32_e32 v96, v98
	v_cvt_pk_bf16_f32 v103, v172, v176
	v_permlane32_swap_b32_e32 v100, v102
	v_cvt_pk_bf16_f32 v104, v145, v149
	v_cvt_pk_bf16_f32 v105, v146, v166
	v_cvt_pk_bf16_f32 v106, v147, v167
	v_cvt_pk_bf16_f32 v107, v148, v168
	v_cvt_pk_bf16_f32 v108, v99, v108
	v_cvt_pk_bf16_f32 v109, v109, v110
	v_cvt_pk_bf16_f32 v110, v111, v112
	v_cvt_pk_bf16_f32 v111, v113, v118
	v_cvt_pk_bf16_f32 v112, v116, v117
	v_cvt_pk_bf16_f32 v113, v119, v122
	v_cvt_pk_bf16_f32 v114, v120, v121
	v_cvt_pk_bf16_f32 v115, v123, v115
	v_permlane32_swap_b32_e32 v101, v103
	v_permlane32_swap_b32_e32 v104, v106
	v_permlane32_swap_b32_e32 v105, v107
	v_permlane32_swap_b32_e32 v108, v110
	v_permlane32_swap_b32_e32 v109, v111
	v_permlane32_swap_b32_e32 v112, v114
	v_permlane32_swap_b32_e32 v113, v115
	ds_read_b64_tr_b16 v[116:117], v160 offset:0
	ds_read_b64_tr_b16 v[118:119], v160 offset:0x800
	ds_read_b64_tr_b16 v[120:121], v160 offset:0x1000
	ds_read_b64_tr_b16 v[122:123], v160 offset:0x1800
	ds_read_b64_tr_b16 v[124:125], v160 offset:0x2000
	ds_read_b64_tr_b16 v[126:127], v160 offset:0x2800
	ds_read_b64_tr_b16 v[138:139], v160 offset:0x3000
	ds_read_b64_tr_b16 v[140:141], v160 offset:0x3800
	s_waitcnt lgkmcnt(0)
; #define SBAR() __builtin_amdgcn_sched_barrier(0)
; #define RESC(a) do { if (__any((a) < 1.f)) { if (hi == 0) al_l[r32] = (a); asm volatile("s_waitcnt lgkmcnt(0)" ::: "memory"); \
;     _Pragma("unroll") for (int d = 0; d < 4; ++d) _Pragma("unroll") for (int r = 0; r < 16; ++r) o[d][r] *= al_l[crow(r, hi)]; } } while (0)
; template <int D0> __device__ __forceinline__ void pv_one(f32x16& od, int vb, bf16x8 pa0, bf16x8 pa1, bf16x8 pa2, bf16x8 pa3) {
;     const s16x4 l0 = tr_read<v_rd_off(D0, 0, 0)>(vb), h0 = tr_read<v_rd_off(D0, 0, 1)>(vb), l1 = tr_read<v_rd_off(D0, 1, 0)>(vb), h1 = tr_read<v_rd_off(D0, 1, 1)>(vb);
;     const s16x4 l2 = tr_read<v_rd_off(D0, 2, 0)>(vb), h2 = tr_read<v_rd_off(D0, 2, 1)>(vb), l3 = tr_read<v_rd_off(D0, 3, 0)>(vb), h3 = tr_read<v_rd_off(D0, 3, 1)>(vb);
;     asm volatile("s_waitcnt lgkmcnt(0)" ::: "memory"); SBAR();
;     ...
;     od = __builtin_amdgcn_mfma_f32_32x32x16_bf16(pa0, PK(l0, h0), od, 0, 0, 0);
;     od = __builtin_amdgcn_mfma_f32_32x32x16_bf16(pa1, PK(l1, h1), od, 0, 0, 0);
;     od = __builtin_amdgcn_mfma_f32_32x32x16_bf16(pa2, PK(l2, h2), od, 0, 0, 0);
;     od = __builtin_amdgcn_mfma_f32_32x32x16_bf16(pa3, PK(l3, h3), od, 0, 0, 0);
;     ...
; }
; __device__ __forceinline__ void pv_d0(f32x16* o, int vb, bf16x8 pa0, bf16x8 pa1, bf16x8 pa2, bf16x8 pa3) {
;     pv_one<0>(o[0], vb, pa0, pa1, pa2, pa3); pv_one<1>(o[1], vb, pa0, pa1, pa2, pa3); pv_one<2>(o[2], vb, pa0, pa1, pa2, pa3); pv_one<3>(o[3], vb, pa0, pa1, pa2, pa3);
; }
; __device__ __forceinline__ void attn_unit(const bf16_t* Qb, const bf16_t* Kh, const bf16_t* Vh, bf16_t* Ob, float* scr, int seq, float lam, float onemli, const float* subg, char* lds) {
;     ...
;         pv_d0(o, vb0, pa0, pa1, pa2, pa3); partialSM(pB0, pB1, m_reg, mnB, alB);
;         __syncthreads(); RESC(alB);
	s_nop 0
	v_mfma_f32_32x32x16_bf16 v[48:63], v[100:103], v[116:119], v[48:63]
	ds_read_b64_tr_b16 v[116:117], v160 offset:0x200
	ds_read_b64_tr_b16 v[118:119], v160 offset:0xa00
	v_mfma_f32_32x32x16_bf16 v[48:63], v[104:107], v[120:123], v[48:63]
	ds_read_b64_tr_b16 v[120:121], v160 offset:0x1200
	ds_read_b64_tr_b16 v[122:123], v160 offset:0x1a00
	v_mfma_f32_32x32x16_bf16 v[48:63], v[108:111], v[124:127], v[48:63]
	ds_read_b64_tr_b16 v[124:125], v160 offset:0x2200
	ds_read_b64_tr_b16 v[126:127], v160 offset:0x2a00
	v_mfma_f32_32x32x16_bf16 v[48:63], v[112:115], v[138:141], v[48:63]
	ds_read_b64_tr_b16 v[138:139], v160 offset:0x3200
	ds_read_b64_tr_b16 v[140:141], v160 offset:0x3a00
	s_waitcnt lgkmcnt(0)
	v_mfma_f32_32x32x16_bf16 v[32:47], v[100:103], v[116:119], v[32:47]
	ds_read_b64_tr_b16 v[116:117], v160 offset:0x400
	ds_read_b64_tr_b16 v[118:119], v160 offset:0xc00
	v_mfma_f32_32x32x16_bf16 v[32:47], v[104:107], v[120:123], v[32:47]
	ds_read_b64_tr_b16 v[120:121], v160 offset:0x1400
	ds_read_b64_tr_b16 v[122:123], v160 offset:0x1c00
	v_mfma_f32_32x32x16_bf16 v[32:47], v[108:111], v[124:127], v[32:47]
	ds_read_b64_tr_b16 v[124:125], v160 offset:0x2400
	ds_read_b64_tr_b16 v[126:127], v160 offset:0x2c00
	v_mfma_f32_32x32x16_bf16 v[32:47], v[112:115], v[138:141], v[32:47]
	ds_read_b64_tr_b16 v[138:139], v160 offset:0x3400
	ds_read_b64_tr_b16 v[140:141], v160 offset:0x3c00
	s_waitcnt lgkmcnt(0)
	v_mfma_f32_32x32x16_bf16 v[16:31], v[100:103], v[116:119], v[16:31]
	ds_read_b64_tr_b16 v[116:117], v160 offset:0x600
	ds_read_b64_tr_b16 v[118:119], v160 offset:0xe00
	v_mfma_f32_32x32x16_bf16 v[16:31], v[104:107], v[120:123], v[16:31]
	ds_read_b64_tr_b16 v[120:121], v160 offset:0x1600
	ds_read_b64_tr_b16 v[122:123], v160 offset:0x1e00
	v_mfma_f32_32x32x16_bf16 v[16:31], v[108:111], v[124:127], v[16:31]
	ds_read_b64_tr_b16 v[124:125], v160 offset:0x2600
	ds_read_b64_tr_b16 v[126:127], v160 offset:0x2e00
	v_mfma_f32_32x32x16_bf16 v[16:31], v[112:115], v[138:141], v[16:31]
	ds_read_b64_tr_b16 v[138:139], v160 offset:0x3600
	ds_read_b64_tr_b16 v[140:141], v160 offset:0x3e00
	s_waitcnt lgkmcnt(0)
	v_mfma_f32_32x32x16_bf16 v[0:15], v[100:103], v[116:119], v[0:15]
	v_max_f32_e32 v99, v81, v81
	v_max_f32_e32 v100, v80, v80
	v_max_f32_e32 v99, v100, v99
	v_max3_f32 v99, v99, v82, v83
	v_max3_f32 v99, v99, v84, v85
	v_max3_f32 v99, v99, v86, v87
	v_max3_f32 v99, v99, v88, v89
	v_max3_f32 v99, v99, v90, v91
	v_max3_f32 v99, v99, v92, v93
	v_mfma_f32_32x32x16_bf16 v[0:15], v[104:107], v[120:123], v[0:15]
	v_max3_f32 v99, v99, v94, v95
	v_max3_f32 v99, v99, v64, v65
	v_max3_f32 v99, v99, v66, v67
	v_max3_f32 v99, v99, v68, v69
	v_max3_f32 v99, v99, v70, v71
	v_max3_f32 v99, v99, v72, v73
	v_max3_f32 v99, v99, v74, v75
	v_max3_f32 v99, v99, v76, v77
	v_mfma_f32_32x32x16_bf16 v[0:15], v[108:111], v[124:127], v[0:15]
	v_max3_f32 v99, v99, v78, v79
	v_mov_b32_e32 v100, v99
	s_nop 1
	v_permlane32_swap_b32_e32 v99, v100
	v_max_f32_e32 v100, v100, v100
	v_max_f32_e32 v99, v99, v99
	v_max_f32_e32 v99, v99, v100
	v_sub_f32_e32 v100, v99, v134
	v_cmp_ge_f32_e32 vcc, s65, v100
	v_max_f32_e32 v100, v134, v134
	v_max_f32_e32 v100, v100, v99
	v_mfma_f32_32x32x16_bf16 v[0:15], v[112:115], v[138:141], v[0:15]
	v_sub_f32_e32 v99, v134, v100
	v_mul_f32_e32 v99, 0x3e38aa3b, v99
	v_exp_f32_e32 v99, v99
	s_cmp_eq_u64 vcc, exec
	s_cselect_b64 s[8:9], -1, 0
	v_cndmask_b32_e64 v99, v99, 1.0, s[8:9]
	v_cmp_gt_f32_e32 vcc, 1.0, v99
	s_barrier
	s_cbranch_vccz .LBB0_294
	s_and_saveexec_b64 s[2:3], s[6:7]
	ds_write_b32 v157, v99 offset:128
	s_or_b64 exec, exec, s[2:3]
	s_waitcnt lgkmcnt(0)
	ds_read_b128 v[102:105], v158 offset:224
	ds_read_b128 v[106:109], v158 offset:192
	ds_read_b128 v[110:113], v158 offset:160
	ds_read_b128 v[114:117], v158 offset:128
	s_waitcnt lgkmcnt(3)
	v_pk_mul_f32 v[62:63], v[62:63], v[104:105]
	s_waitcnt lgkmcnt(2)
	v_pk_mul_f32 v[58:59], v[58:59], v[108:109]
	s_waitcnt lgkmcnt(1)
	v_pk_mul_f32 v[54:55], v[54:55], v[112:113]
	s_waitcnt lgkmcnt(0)
	v_pk_mul_f32 v[50:51], v[50:51], v[116:117]
	v_pk_mul_f32 v[60:61], v[60:61], v[102:103]
	v_pk_mul_f32 v[56:57], v[56:57], v[106:107]
	v_pk_mul_f32 v[52:53], v[52:53], v[110:111]
	v_pk_mul_f32 v[48:49], v[48:49], v[114:115]
	v_pk_mul_f32 v[46:47], v[46:47], v[104:105]
	v_pk_mul_f32 v[42:43], v[42:43], v[108:109]
	v_pk_mul_f32 v[38:39], v[38:39], v[112:113]
	v_pk_mul_f32 v[34:35], v[34:35], v[116:117]
	v_pk_mul_f32 v[44:45], v[44:45], v[102:103]
	v_pk_mul_f32 v[40:41], v[40:41], v[106:107]
	v_pk_mul_f32 v[36:37], v[36:37], v[110:111]
	v_pk_mul_f32 v[32:33], v[32:33], v[114:115]
	v_pk_mul_f32 v[30:31], v[30:31], v[104:105]
	v_pk_mul_f32 v[26:27], v[26:27], v[108:109]
	v_pk_mul_f32 v[22:23], v[22:23], v[112:113]
	v_pk_mul_f32 v[18:19], v[18:19], v[116:117]
	v_pk_mul_f32 v[28:29], v[28:29], v[102:103]
	v_pk_mul_f32 v[24:25], v[24:25], v[106:107]
	v_pk_mul_f32 v[20:21], v[20:21], v[110:111]
	v_pk_mul_f32 v[16:17], v[16:17], v[114:115]
	v_pk_mul_f32 v[14:15], v[14:15], v[104:105]
	v_pk_mul_f32 v[10:11], v[10:11], v[108:109]
	v_pk_mul_f32 v[6:7], v[6:7], v[112:113]
	v_pk_mul_f32 v[2:3], v[2:3], v[116:117]
	v_pk_mul_f32 v[12:13], v[12:13], v[102:103]
	v_pk_mul_f32 v[8:9], v[8:9], v[106:107]
	v_pk_mul_f32 v[4:5], v[4:5], v[110:111]
	v_pk_mul_f32 v[0:1], v[0:1], v[114:115]
